# EpiS2 (P2 S5 output GEMM): the 16 serial u-piece loads issued up front into dead fragment VGPRs, copied per piece under counted vmcnt(15)
# speedup vs baseline: 1.0020x; 1.0018x over previous
; #define EPI_OPAQUE(x) asm volatile("" : "+v"(x))
;     __device__ __forceinline__ void operator()(const f32x4 (&acc)[2][2][4][2], const Unit& u, int wr, int wc, int fr, int fq, const EpiCtx& X) const {
;         const bool odd = fr & 1; const int fe = fr - (fr & 1), o32 = (fr & 1) * 32;
;         const int g = u.pn; const int p0 = 8 * (fq & 1);
;         const f32x4 d0 = *(const f32x4*)(dvec + g * 16 + p0), d1 = *(const f32x4*)(dvec + g * 16 + p0 + 4);
;         const char* ub = (const char*)(UA + (size_t)u.pm * BM * UA_LD);
;         unsigned ulo = (unsigned)((wr * 64 + fe) * UA_LD + wc * 64 + o32 + 8 * fq) * 2u; EPI_OPAQUE(ulo);
;         char* gb = (char*)(GACT + (size_t)(u.pm & 3) * 256 * 16 * W_SSM + g * 16);
;         unsigned glo = (unsigned)(((wr * 64 + fe) * 16 + wc * 4 + (fr & 1) * 2 + (fq >> 1)) * W_SSM + p0) * 2u; EPI_OPAQUE(glo);
;     ...
;         EPI_PIECES({ const unsigned uoff = ulo + (unsigned)(rl * UA_LD) * 2u, goff = glo + (unsigned)(rl * 16 * W_SSM) * 2u;
;             S2_ONE(p1a, p1b, uoff, goff); S2_ONE(p2a, p2b, uoff + UA_LD * 2, goff + 16 * W_SSM * 2); })
.LBB0_285:
	s_lshl_b32 s12, s12, 4
	s_ashr_i32 s13, s12, 31
	s_mul_i32 s22, s35, 0x30000
	s_mul_hi_i32 s23, s35, 0x30000
	s_add_u32 s22, s44, s22
	v_lshl_add_u64 v[44:45], s[12:13], 2, v[144:145]
	s_addc_u32 s23, s45, s23
	v_mov_b32_e32 v157, v151
	v_mov_b32_e32 v156, v152
	global_load_dwordx4 v[40:43], v[44:45], off offset:16
	s_nop 0
	global_load_dwordx4 v[44:47], v[44:45], off
	global_load_dwordx4 v[158:161], v157, s[22:23]
	v_add_u32_e32 v178, 0x300, v157
	global_load_dwordx4 v[180:183], v178, s[22:23]
	v_add_u32_e32 v179, 0x3000, v157
	global_load_dwordx4 v[184:187], v179, s[22:23]
	v_add_u32_e32 v178, 0x3300, v157
	global_load_dwordx4 v[188:191], v178, s[22:23]
	v_add_u32_e32 v179, 0x6000, v157
	global_load_dwordx4 v[192:195], v179, s[22:23]
	v_add_u32_e32 v178, 0x6300, v157
	global_load_dwordx4 v[196:199], v178, s[22:23]
	v_add_u32_e32 v179, 0x9000, v157
	global_load_dwordx4 v[200:203], v179, s[22:23]
	v_add_u32_e32 v178, 0x9300, v157
	global_load_dwordx4 v[204:207], v178, s[22:23]
	v_add_u32_e32 v179, 0x18000, v157
	global_load_dwordx4 v[208:211], v179, s[22:23]
	v_add_u32_e32 v178, 0x18300, v157
	global_load_dwordx4 v[220:223], v178, s[22:23]
	v_add_u32_e32 v179, 0x1b000, v157
	global_load_dwordx4 v[224:227], v179, s[22:23]
	v_add_u32_e32 v178, 0x1b300, v157
	global_load_dwordx4 v[228:231], v178, s[22:23]
	v_add_u32_e32 v179, 0x1e000, v157
	global_load_dwordx4 v[232:235], v179, s[22:23]
	v_add_u32_e32 v178, 0x1e300, v157
	global_load_dwordx4 v[236:239], v178, s[22:23]
	v_add_u32_e32 v179, 0x21000, v157
	global_load_dwordx4 v[240:243], v179, s[22:23]
	v_add_u32_e32 v178, 0x21300, v157
	global_load_dwordx4 v[244:247], v178, s[22:23]
	v_cndmask_b32_e64 v164, v133, v125, s[8:9]
	v_mov_b32_e32 v167, 0
	v_cndmask_b32_e64 v162, v135, v127, s[8:9]
	v_mov_b32_e32 v169, 0
	v_mov_b32_dpp v167, v164 quad_perm:[1,0,3,2] row_mask:0xf bank_mask:0xf
	v_cndmask_b32_e64 v163, v134, v126, s[8:9]
	v_cndmask_b32_e64 v165, v132, v124, s[8:9]
	v_mov_b32_e32 v166, 0
	v_mov_b32_e32 v168, 0
	v_mov_b32_dpp v169, v162 quad_perm:[1,0,3,2] row_mask:0xf bank_mask:0xf
	v_cndmask_b32_e64 v133, v167, v133, s[8:9]
	v_mov_b32_dpp v166, v165 quad_perm:[1,0,3,2] row_mask:0xf bank_mask:0xf
	v_mov_b32_dpp v168, v163 quad_perm:[1,0,3,2] row_mask:0xf bank_mask:0xf
	v_cndmask_b32_e64 v135, v169, v135, s[8:9]
	v_cndmask_b32_e64 v132, v166, v132, s[8:9]
	v_cndmask_b32_e64 v170, v131, v123, s[8:9]
	v_cndmask_b32_e64 v173, v128, v120, s[8:9]
	v_mov_b32_e32 v174, 0
	v_mov_b32_e32 v177, 0
	v_cndmask_b32_e64 v171, v130, v122, s[8:9]
	v_cndmask_b32_e64 v172, v129, v121, s[8:9]
	v_mov_b32_e32 v175, 0
	v_mov_b32_e32 v176, 0
	v_mov_b32_dpp v174, v173 quad_perm:[1,0,3,2] row_mask:0xf bank_mask:0xf
	v_mov_b32_dpp v177, v170 quad_perm:[1,0,3,2] row_mask:0xf bank_mask:0xf
	v_mov_b32_dpp v175, v172 quad_perm:[1,0,3,2] row_mask:0xf bank_mask:0xf
	v_mov_b32_dpp v176, v171 quad_perm:[1,0,3,2] row_mask:0xf bank_mask:0xf
	v_cndmask_b32_e64 v131, v177, v131, s[8:9]
	v_cndmask_b32_e64 v128, v174, v128, s[8:9]
	v_cndmask_b32_e64 v134, v168, v134, s[8:9]
	v_cndmask_b32_e64 v130, v176, v130, s[8:9]
	v_cndmask_b32_e64 v129, v175, v129, s[8:9]
	s_lshl_b32 s24, s35, 24
	s_and_b32 s24, s24, 0x3000000
	s_add_u32 s24, s59, s24
	s_addc_u32 s25, s60, 0
	s_lshl_b64 s[12:13], s[12:13], 1
	s_add_u32 s12, s24, s12
	s_addc_u32 s13, s25, s13
	v_cndmask_b32_e64 v124, v124, v166, s[8:9]
	v_cndmask_b32_e64 v125, v125, v167, s[8:9]
	v_cndmask_b32_e64 v127, v127, v169, s[8:9]
	v_cndmask_b32_e64 v121, v121, v175, s[8:9]
	v_cndmask_b32_e64 v120, v120, v174, s[8:9]
	v_cndmask_b32_e64 v123, v123, v177, s[8:9]
	v_cndmask_b32_e64 v126, v126, v168, s[8:9]
	v_cndmask_b32_e64 v122, v122, v176, s[8:9]
	s_and_b64 vcc, exec, s[10:11]
	s_mov_b64 s[10:11], -1
	s_waitcnt vmcnt(15)
	v_lshlrev_b32_e32 v162, 16, v158
	v_and_b32_e32 v158, 0xffff0000, v158
	v_lshlrev_b32_e32 v163, 16, v159
	v_and_b32_e32 v159, 0xffff0000, v159
	v_fmac_f32_e32 v133, v45, v158
	v_fmac_f32_e32 v135, v47, v159
	v_mul_f32_e32 v159, 0x3d372713, v133
	v_fmac_f32_e32 v132, v44, v162
	v_mul_f32_e32 v159, v133, v159
	v_mul_f32_e32 v158, 0x3d372713, v132
	v_fma_f32 v159, v133, v159, v133
	v_mul_f32_e32 v158, v132, v158
	v_mul_f32_e32 v159, 0x3f4c422a, v159
	v_fma_f32 v158, v132, v158, v132
	v_add_f32_e32 v159, v159, v159
	v_mul_f32_e32 v158, 0x3f4c422a, v158
	v_mul_f32_e32 v159, 0xbfb8aa3b, v159
	v_add_f32_e32 v158, v158, v158
	v_exp_f32_e32 v159, v159
	v_mul_f32_e32 v158, 0xbfb8aa3b, v158
	v_exp_f32_e32 v158, v158
	v_lshlrev_b32_e32 v164, 16, v160
	v_add_f32_e32 v159, 1.0, v159
	v_rcp_f32_e32 v159, v159
	v_add_f32_e32 v158, 1.0, v158
	v_rcp_f32_e32 v158, v158
	v_fmac_f32_e32 v128, v40, v164
	v_mul_f32_e32 v133, v133, v159
	v_and_b32_e32 v159, 0xffff0000, v160
	v_lshlrev_b32_e32 v160, 16, v161
	v_and_b32_e32 v161, 0xffff0000, v161
	v_fmac_f32_e32 v131, v43, v161
	v_fmac_f32_e32 v134, v46, v163
	v_mul_f32_e32 v132, v132, v158
	v_mul_f32_e32 v158, 0x3d372713, v128
	v_fmac_f32_e32 v129, v41, v159
	v_fmac_f32_e32 v130, v42, v160
	v_mul_f32_e32 v161, 0x3d372713, v131
	v_mul_f32_e32 v162, 0x3d372713, v134
	v_mul_f32_e32 v163, 0x3d372713, v135
	v_mul_f32_e32 v158, v128, v158
	v_mul_f32_e32 v159, 0x3d372713, v129
	v_mul_f32_e32 v160, 0x3d372713, v130
	v_mul_f32_e32 v161, v131, v161
	v_mul_f32_e32 v162, v134, v162
	v_mul_f32_e32 v163, v135, v163
	v_fma_f32 v158, v128, v158, v128
	v_mul_f32_e32 v159, v129, v159
	v_mul_f32_e32 v160, v130, v160
	v_fma_f32 v161, v131, v161, v131
	v_fma_f32 v162, v134, v162, v134
	v_fma_f32 v163, v135, v163, v135
	v_mul_f32_e32 v158, 0x3f4c422a, v158
	v_fma_f32 v159, v129, v159, v129
	v_fma_f32 v160, v130, v160, v130
	v_mul_f32_e32 v161, 0x3f4c422a, v161
;     __device__ __forceinline__ void operator()(const f32x4 (&acc)[2][2][4][2], const Unit& u, int wr, int wc, int fr, int fq, const EpiCtx& X) const {
;     ...
;         EPI_PIECES({ const unsigned uoff = ulo + (unsigned)(rl * UA_LD) * 2u, goff = glo + (unsigned)(rl * 16 * W_SSM) * 2u;
;             S2_ONE(p1a, p1b, uoff, goff); S2_ONE(p2a, p2b, uoff + UA_LD * 2, goff + 16 * W_SSM * 2); })
	v_mul_f32_e32 v162, 0x3f4c422a, v162
	v_mul_f32_e32 v163, 0x3f4c422a, v163
	v_add_f32_e32 v158, v158, v158
	v_mul_f32_e32 v159, 0x3f4c422a, v159
	v_mul_f32_e32 v160, 0x3f4c422a, v160
	v_add_f32_e32 v161, v161, v161
	v_add_f32_e32 v162, v162, v162
	v_add_f32_e32 v163, v163, v163
	v_mul_f32_e32 v158, 0xbfb8aa3b, v158
	v_add_f32_e32 v159, v159, v159
	v_add_f32_e32 v160, v160, v160
	v_mul_f32_e32 v161, 0xbfb8aa3b, v161
	v_mul_f32_e32 v162, 0xbfb8aa3b, v162
	v_mul_f32_e32 v163, 0xbfb8aa3b, v163
	v_exp_f32_e32 v158, v158
	v_mul_f32_e32 v159, 0xbfb8aa3b, v159
	v_mul_f32_e32 v160, 0xbfb8aa3b, v160
	v_exp_f32_e32 v161, v161
	v_exp_f32_e32 v162, v162
	v_exp_f32_e32 v163, v163
	v_exp_f32_e32 v159, v159
	v_exp_f32_e32 v160, v160
	v_add_f32_e32 v158, 1.0, v158
	v_add_f32_e32 v161, 1.0, v161
	v_add_f32_e32 v162, 1.0, v162
	v_add_f32_e32 v163, 1.0, v163
	v_rcp_f32_e32 v158, v158
	v_add_f32_e32 v159, 1.0, v159
	v_add_f32_e32 v160, 1.0, v160
	v_rcp_f32_e32 v161, v161
	v_rcp_f32_e32 v162, v162
	v_rcp_f32_e32 v163, v163
	v_rcp_f32_e32 v159, v159
	v_rcp_f32_e32 v160, v160
	v_mul_f32_e32 v158, v128, v158
	v_mul_f32_e32 v131, v131, v161
	v_cvt_pk_bf16_f32 v128, v132, v133
	v_mul_f32_e32 v134, v134, v162
	v_mul_f32_e32 v135, v135, v163
	v_mul_f32_e32 v159, v129, v159
	v_mul_f32_e32 v160, v130, v160
	v_cvt_pk_bf16_f32 v129, v134, v135
	v_cvt_pk_bf16_f32 v130, v158, v159
	v_cvt_pk_bf16_f32 v131, v160, v131
	global_store_dwordx4 v156, v[128:131], s[12:13]
	s_nop 1
	v_add_u32_e32 v128, 0x300, v157
	s_waitcnt vmcnt(15)
	s_nop 1
	v_mov_b32_e32 v128, v180
	v_mov_b32_e32 v129, v181
	v_mov_b32_e32 v130, v182
	v_mov_b32_e32 v131, v183
	v_lshlrev_b32_e32 v132, 16, v128
	v_and_b32_e32 v128, 0xffff0000, v128
	v_fmac_f32_e32 v124, v44, v132
	v_fmac_f32_e32 v125, v45, v128
	v_mul_f32_e32 v128, 0x3d372713, v124
	v_mul_f32_e32 v128, v124, v128
	v_fma_f32 v128, v124, v128, v124
	v_lshlrev_b32_e32 v133, 16, v129
	v_mul_f32_e32 v128, 0x3f4c422a, v128
	v_and_b32_e32 v129, 0xffff0000, v129
	v_add_f32_e32 v128, v128, v128
	v_fmac_f32_e32 v127, v47, v129
	v_mul_f32_e32 v128, 0xbfb8aa3b, v128
	v_mul_f32_e32 v129, 0x3d372713, v127
	v_exp_f32_e32 v128, v128
	v_mul_f32_e32 v129, v127, v129
	v_fma_f32 v129, v127, v129, v127
	v_mul_f32_e32 v129, 0x3f4c422a, v129
	v_add_f32_e32 v129, v129, v129
	v_add_f32_e32 v128, 1.0, v128
	v_mul_f32_e32 v129, 0xbfb8aa3b, v129
	v_rcp_f32_e32 v128, v128
	v_exp_f32_e32 v129, v129
	v_fmac_f32_e32 v126, v46, v133
	v_mul_f32_e32 v132, 0x3d372713, v125
	v_mul_f32_e32 v124, v124, v128
	v_add_f32_e32 v128, 1.0, v129
	v_lshlrev_b32_e32 v129, 16, v130
	v_and_b32_e32 v130, 0xffff0000, v130
	v_fmac_f32_e32 v120, v40, v129
	v_fmac_f32_e32 v121, v41, v130
	v_mul_f32_e32 v129, 0x3d372713, v120
	v_mul_f32_e32 v130, 0x3d372713, v121
	v_mul_f32_e32 v129, v120, v129
	v_mul_f32_e32 v130, v121, v130
	v_fma_f32 v129, v120, v129, v120
	v_fma_f32 v130, v121, v130, v121
	v_mul_f32_e32 v129, 0x3f4c422a, v129
	v_mul_f32_e32 v130, 0x3f4c422a, v130
	v_add_f32_e32 v129, v129, v129
	v_add_f32_e32 v130, v130, v130
	v_mul_f32_e32 v129, 0xbfb8aa3b, v129
	v_mul_f32_e32 v130, 0xbfb8aa3b, v130
	v_rcp_f32_e32 v128, v128
	v_exp_f32_e32 v129, v129
	v_exp_f32_e32 v130, v130
	v_mul_f32_e32 v133, 0x3d372713, v126
	v_mul_f32_e32 v127, v127, v128
	v_add_f32_e32 v128, 1.0, v129
	v_add_f32_e32 v129, 1.0, v130
	v_lshlrev_b32_e32 v130, 16, v131
	v_and_b32_e32 v131, 0xffff0000, v131
	v_fmac_f32_e32 v123, v43, v131
	v_fmac_f32_e32 v122, v42, v130
	v_mul_f32_e32 v131, 0x3d372713, v123
	v_mul_f32_e32 v132, v125, v132
	v_mul_f32_e32 v130, 0x3d372713, v122
	v_mul_f32_e32 v131, v123, v131
	v_mul_f32_e32 v133, v126, v133
	v_fma_f32 v132, v125, v132, v125
	v_mul_f32_e32 v130, v122, v130
	v_fma_f32 v131, v123, v131, v123
	v_fma_f32 v133, v126, v133, v126
	v_mul_f32_e32 v132, 0x3f4c422a, v132
	v_fma_f32 v130, v122, v130, v122
	v_mul_f32_e32 v131, 0x3f4c422a, v131
	v_mul_f32_e32 v133, 0x3f4c422a, v133
	v_add_f32_e32 v132, v132, v132
	v_mul_f32_e32 v130, 0x3f4c422a, v130
	v_add_f32_e32 v131, v131, v131
	v_add_f32_e32 v133, v133, v133
	v_mul_f32_e32 v132, 0xbfb8aa3b, v132
	v_add_f32_e32 v130, v130, v130
	v_mul_f32_e32 v131, 0xbfb8aa3b, v131
	v_mul_f32_e32 v133, 0xbfb8aa3b, v133
	v_exp_f32_e32 v132, v132
	v_mul_f32_e32 v130, 0xbfb8aa3b, v130
	v_exp_f32_e32 v131, v131
	v_exp_f32_e32 v133, v133
	v_exp_f32_e32 v130, v130
	v_add_f32_e32 v132, 1.0, v132
	v_add_f32_e32 v131, 1.0, v131
	v_add_f32_e32 v133, 1.0, v133
	v_rcp_f32_e32 v132, v132
	v_rcp_f32_e32 v128, v128
	v_add_f32_e32 v130, 1.0, v130
	v_rcp_f32_e32 v131, v131
	v_rcp_f32_e32 v133, v133
	v_rcp_f32_e32 v129, v129
	v_rcp_f32_e32 v130, v130
	v_mul_f32_e32 v125, v125, v132
	v_mul_f32_e32 v128, v120, v128
	v_mul_f32_e32 v123, v123, v131
	v_cvt_pk_bf16_f32 v120, v124, v125
	v_add_u32_e32 v124, 0x10000, v156
	v_mul_f32_e32 v126, v126, v133
	v_mul_f32_e32 v129, v121, v129
	v_mul_f32_e32 v130, v122, v130
	v_cvt_pk_bf16_f32 v121, v126, v127
	v_cvt_pk_bf16_f32 v122, v128, v129
	v_cvt_pk_bf16_f32 v123, v130, v123
	global_store_dwordx4 v124, v[120:123], s[12:13]
	v_cndmask_b32_e64 v127, v116, v108, s[8:9]
	v_mov_b32_e32 v128, 0
	v_add_u32_e32 v120, 0x3000, v157
	s_waitcnt vmcnt(15)
;     __device__ __forceinline__ void operator()(const f32x4 (&acc)[2][2][4][2], const Unit& u, int wr, int wc, int fr, int fq, const EpiCtx& X) const {
;     ...
;         EPI_PIECES({ const unsigned uoff = ulo + (unsigned)(rl * UA_LD) * 2u, goff = glo + (unsigned)(rl * 16 * W_SSM) * 2u;
;             S2_ONE(p1a, p1b, uoff, goff); S2_ONE(p2a, p2b, uoff + UA_LD * 2, goff + 16 * W_SSM * 2); })
	s_nop 1
	v_mov_b32_e32 v120, v184
	v_mov_b32_e32 v121, v185
	v_mov_b32_e32 v122, v186
	v_mov_b32_e32 v123, v187
	v_cndmask_b32_e64 v126, v117, v109, s[8:9]
	v_mov_b32_dpp v128, v127 quad_perm:[1,0,3,2] row_mask:0xf bank_mask:0xf
	v_mov_b32_e32 v127, 0
	v_cndmask_b32_e64 v131, v112, v104, s[8:9]
	v_mov_b32_e32 v132, 0
	v_cndmask_b32_e64 v125, v118, v110, s[8:9]
	v_mov_b32_dpp v127, v126 quad_perm:[1,0,3,2] row_mask:0xf bank_mask:0xf
	v_mov_b32_e32 v126, 0
	v_cndmask_b32_e64 v130, v113, v105, s[8:9]
	v_mov_b32_dpp v132, v131 quad_perm:[1,0,3,2] row_mask:0xf bank_mask:0xf
	v_mov_b32_e32 v131, 0
	v_cndmask_b32_e64 v124, v119, v111, s[8:9]
	v_mov_b32_dpp v126, v125 quad_perm:[1,0,3,2] row_mask:0xf bank_mask:0xf
	v_mov_b32_e32 v125, 0
	v_cndmask_b32_e64 v129, v114, v106, s[8:9]
	v_mov_b32_dpp v131, v130 quad_perm:[1,0,3,2] row_mask:0xf bank_mask:0xf
	v_mov_b32_e32 v130, 0
	v_mov_b32_dpp v125, v124 quad_perm:[1,0,3,2] row_mask:0xf bank_mask:0xf
	v_cndmask_b32_e64 v124, v115, v107, s[8:9]
	v_mov_b32_dpp v130, v129 quad_perm:[1,0,3,2] row_mask:0xf bank_mask:0xf
	v_mov_b32_e32 v129, 0
	v_cndmask_b32_e64 v117, v127, v117, s[8:9]
	v_cndmask_b32_e64 v119, v125, v119, s[8:9]
	v_mov_b32_dpp v129, v124 quad_perm:[1,0,3,2] row_mask:0xf bank_mask:0xf
	v_cndmask_b32_e64 v113, v131, v113, s[8:9]
	v_cndmask_b32_e64 v112, v132, v112, s[8:9]
	v_cndmask_b32_e64 v116, v128, v116, s[8:9]
	v_cndmask_b32_e64 v115, v129, v115, s[8:9]
	v_cndmask_b32_e64 v118, v126, v118, s[8:9]
	v_cndmask_b32_e64 v114, v130, v114, s[8:9]
	v_add_u32_e32 v133, 0x100000, v156
	v_cndmask_b32_e64 v109, v109, v127, s[8:9]
	v_cndmask_b32_e64 v111, v111, v125, s[8:9]
	v_cndmask_b32_e64 v105, v105, v131, s[8:9]
	v_cndmask_b32_e64 v104, v104, v132, s[8:9]
	v_cndmask_b32_e64 v108, v108, v128, s[8:9]
	v_cndmask_b32_e64 v107, v107, v129, s[8:9]
	v_cndmask_b32_e64 v110, v110, v126, s[8:9]
	v_cndmask_b32_e64 v106, v106, v130, s[8:9]
	v_lshlrev_b32_e32 v124, 16, v120
	v_and_b32_e32 v120, 0xffff0000, v120
	v_fmac_f32_e32 v117, v45, v120
	v_mul_f32_e32 v120, 0x3d372713, v117
	v_mul_f32_e32 v120, v117, v120
	v_fma_f32 v120, v117, v120, v117
	v_mul_f32_e32 v120, 0x3f4c422a, v120
	v_lshlrev_b32_e32 v134, 16, v121
	v_and_b32_e32 v121, 0xffff0000, v121
	v_add_f32_e32 v120, v120, v120
	v_fmac_f32_e32 v119, v47, v121
	v_mul_f32_e32 v120, 0xbfb8aa3b, v120
	v_mul_f32_e32 v121, 0x3d372713, v119
	v_exp_f32_e32 v120, v120
	v_mul_f32_e32 v121, v119, v121
	v_fma_f32 v121, v119, v121, v119
	v_mul_f32_e32 v121, 0x3f4c422a, v121
	v_add_f32_e32 v121, v121, v121
	v_add_f32_e32 v120, 1.0, v120
	v_mul_f32_e32 v121, 0xbfb8aa3b, v121
	v_rcp_f32_e32 v120, v120
	v_exp_f32_e32 v121, v121
	v_fmac_f32_e32 v116, v44, v124
	v_mul_f32_e32 v124, 0x3d372713, v116
	v_mul_f32_e32 v117, v117, v120
	v_add_f32_e32 v120, 1.0, v121
	v_lshlrev_b32_e32 v121, 16, v122
	v_and_b32_e32 v122, 0xffff0000, v122
	v_fmac_f32_e32 v112, v40, v121
	v_fmac_f32_e32 v113, v41, v122
	v_mul_f32_e32 v121, 0x3d372713, v112
	v_mul_f32_e32 v122, 0x3d372713, v113
	v_mul_f32_e32 v121, v112, v121
	v_mul_f32_e32 v122, v113, v122
	v_fma_f32 v121, v112, v121, v112
	v_fma_f32 v122, v113, v122, v113
	v_mul_f32_e32 v121, 0x3f4c422a, v121
	v_mul_f32_e32 v122, 0x3f4c422a, v122
	v_add_f32_e32 v121, v121, v121
	v_add_f32_e32 v122, v122, v122
	v_mul_f32_e32 v121, 0xbfb8aa3b, v121
	v_mul_f32_e32 v122, 0xbfb8aa3b, v122
	v_rcp_f32_e32 v120, v120
	v_exp_f32_e32 v121, v121
	v_exp_f32_e32 v122, v122
	v_fmac_f32_e32 v118, v46, v134
	v_mul_f32_e32 v119, v119, v120
	v_add_f32_e32 v120, 1.0, v121
	v_add_f32_e32 v121, 1.0, v122
	v_lshlrev_b32_e32 v122, 16, v123
	v_and_b32_e32 v123, 0xffff0000, v123
	v_fmac_f32_e32 v115, v43, v123
	v_fmac_f32_e32 v114, v42, v122
	v_mul_f32_e32 v123, 0x3d372713, v115
	v_mul_f32_e32 v124, v116, v124
	v_mul_f32_e32 v134, 0x3d372713, v118
	v_mul_f32_e32 v122, 0x3d372713, v114
	v_mul_f32_e32 v123, v115, v123
	v_fma_f32 v124, v116, v124, v116
	v_mul_f32_e32 v134, v118, v134
	v_mul_f32_e32 v122, v114, v122
	v_fma_f32 v123, v115, v123, v115
	v_mul_f32_e32 v124, 0x3f4c422a, v124
	v_fma_f32 v134, v118, v134, v118
	v_fma_f32 v122, v114, v122, v114
	v_mul_f32_e32 v123, 0x3f4c422a, v123
	v_add_f32_e32 v124, v124, v124
	v_mul_f32_e32 v134, 0x3f4c422a, v134
	v_mul_f32_e32 v122, 0x3f4c422a, v122
	v_add_f32_e32 v123, v123, v123
	v_mul_f32_e32 v124, 0xbfb8aa3b, v124
	v_add_f32_e32 v134, v134, v134
	v_add_f32_e32 v122, v122, v122
	v_mul_f32_e32 v123, 0xbfb8aa3b, v123
	v_exp_f32_e32 v124, v124
	v_mul_f32_e32 v134, 0xbfb8aa3b, v134
	v_mul_f32_e32 v122, 0xbfb8aa3b, v122
	v_exp_f32_e32 v123, v123
	v_exp_f32_e32 v134, v134
	v_exp_f32_e32 v122, v122
	v_add_f32_e32 v124, 1.0, v124
	v_add_f32_e32 v123, 1.0, v123
	v_rcp_f32_e32 v124, v124
	v_add_f32_e32 v134, 1.0, v134
	v_rcp_f32_e32 v120, v120
	v_add_f32_e32 v122, 1.0, v122
	v_rcp_f32_e32 v123, v123
	v_rcp_f32_e32 v134, v134
	v_rcp_f32_e32 v121, v121
	v_rcp_f32_e32 v122, v122
	v_mul_f32_e32 v116, v116, v124
	v_mul_f32_e32 v120, v112, v120
	v_mul_f32_e32 v115, v115, v123
	v_cvt_pk_bf16_f32 v112, v116, v117
	v_mul_f32_e32 v118, v118, v134
	v_mul_f32_e32 v121, v113, v121
	v_mul_f32_e32 v122, v114, v122
	v_cvt_pk_bf16_f32 v113, v118, v119
	v_cvt_pk_bf16_f32 v114, v120, v121
	v_cvt_pk_bf16_f32 v115, v122, v115
	global_store_dwordx4 v133, v[112:115], s[12:13]
	s_nop 1
	v_add_u32_e32 v112, 0x3300, v157
	s_waitcnt vmcnt(15)
;     __device__ __forceinline__ void operator()(const f32x4 (&acc)[2][2][4][2], const Unit& u, int wr, int wc, int fr, int fq, const EpiCtx& X) const {
;     ...
;         EPI_PIECES({ const unsigned uoff = ulo + (unsigned)(rl * UA_LD) * 2u, goff = glo + (unsigned)(rl * 16 * W_SSM) * 2u;
;             S2_ONE(p1a, p1b, uoff, goff); S2_ONE(p2a, p2b, uoff + UA_LD * 2, goff + 16 * W_SSM * 2); })
	s_nop 1
	v_mov_b32_e32 v112, v188
	v_mov_b32_e32 v113, v189
	v_mov_b32_e32 v114, v190
	v_mov_b32_e32 v115, v191
	v_lshlrev_b32_e32 v116, 16, v112
	v_and_b32_e32 v112, 0xffff0000, v112
	v_fmac_f32_e32 v109, v45, v112
	v_mul_f32_e32 v112, 0x3d372713, v109
	v_mul_f32_e32 v112, v109, v112
	v_fma_f32 v112, v109, v112, v109
	v_mul_f32_e32 v112, 0x3f4c422a, v112
	v_lshlrev_b32_e32 v117, 16, v113
	v_and_b32_e32 v113, 0xffff0000, v113
	v_add_f32_e32 v112, v112, v112
	v_fmac_f32_e32 v111, v47, v113
	v_mul_f32_e32 v112, 0xbfb8aa3b, v112
	v_mul_f32_e32 v113, 0x3d372713, v111
	v_exp_f32_e32 v112, v112
	v_mul_f32_e32 v113, v111, v113
	v_fma_f32 v113, v111, v113, v111
	v_mul_f32_e32 v113, 0x3f4c422a, v113
	v_add_f32_e32 v113, v113, v113
	v_add_f32_e32 v112, 1.0, v112
	v_mul_f32_e32 v113, 0xbfb8aa3b, v113
	v_rcp_f32_e32 v112, v112
	v_exp_f32_e32 v113, v113
	v_fmac_f32_e32 v108, v44, v116
	v_mul_f32_e32 v116, 0x3d372713, v108
	v_mul_f32_e32 v109, v109, v112
	v_add_f32_e32 v112, 1.0, v113
	v_lshlrev_b32_e32 v113, 16, v114
	v_and_b32_e32 v114, 0xffff0000, v114
	v_fmac_f32_e32 v104, v40, v113
	v_fmac_f32_e32 v105, v41, v114
	v_mul_f32_e32 v113, 0x3d372713, v104
	v_mul_f32_e32 v114, 0x3d372713, v105
	v_mul_f32_e32 v113, v104, v113
	v_mul_f32_e32 v114, v105, v114
	v_fma_f32 v113, v104, v113, v104
	v_fma_f32 v114, v105, v114, v105
	v_mul_f32_e32 v113, 0x3f4c422a, v113
	v_mul_f32_e32 v114, 0x3f4c422a, v114
	v_add_f32_e32 v113, v113, v113
	v_add_f32_e32 v114, v114, v114
	v_mul_f32_e32 v113, 0xbfb8aa3b, v113
	v_mul_f32_e32 v114, 0xbfb8aa3b, v114
	v_rcp_f32_e32 v112, v112
	v_exp_f32_e32 v113, v113
	v_exp_f32_e32 v114, v114
	v_mul_f32_e32 v116, v108, v116
	v_mul_f32_e32 v111, v111, v112
	v_add_f32_e32 v112, 1.0, v113
	v_add_f32_e32 v113, 1.0, v114
	v_lshlrev_b32_e32 v114, 16, v115
	v_and_b32_e32 v115, 0xffff0000, v115
	v_fmac_f32_e32 v107, v43, v115
	v_fmac_f32_e32 v110, v46, v117
	v_fmac_f32_e32 v106, v42, v114
	v_mul_f32_e32 v115, 0x3d372713, v107
	v_fma_f32 v116, v108, v116, v108
	v_mul_f32_e32 v117, 0x3d372713, v110
	v_mul_f32_e32 v114, 0x3d372713, v106
	v_mul_f32_e32 v115, v107, v115
	v_mul_f32_e32 v116, 0x3f4c422a, v116
	v_mul_f32_e32 v117, v110, v117
	v_mul_f32_e32 v114, v106, v114
	v_fma_f32 v115, v107, v115, v107
	v_add_f32_e32 v116, v116, v116
	v_fma_f32 v117, v110, v117, v110
	v_fma_f32 v114, v106, v114, v106
	v_mul_f32_e32 v115, 0x3f4c422a, v115
	v_mul_f32_e32 v116, 0xbfb8aa3b, v116
	v_mul_f32_e32 v117, 0x3f4c422a, v117
	v_mul_f32_e32 v114, 0x3f4c422a, v114
	v_add_f32_e32 v115, v115, v115
	v_exp_f32_e32 v116, v116
	v_add_f32_e32 v117, v117, v117
	v_add_f32_e32 v114, v114, v114
	v_mul_f32_e32 v115, 0xbfb8aa3b, v115
	v_mul_f32_e32 v117, 0xbfb8aa3b, v117
	v_mul_f32_e32 v114, 0xbfb8aa3b, v114
	v_exp_f32_e32 v115, v115
	v_exp_f32_e32 v117, v117
	v_exp_f32_e32 v114, v114
	v_add_f32_e32 v116, 1.0, v116
	v_rcp_f32_e32 v116, v116
	v_add_f32_e32 v115, 1.0, v115
	v_add_f32_e32 v117, 1.0, v117
	v_rcp_f32_e32 v112, v112
	v_add_f32_e32 v114, 1.0, v114
	v_rcp_f32_e32 v115, v115
	v_rcp_f32_e32 v117, v117
	v_rcp_f32_e32 v113, v113
	v_rcp_f32_e32 v114, v114
	v_mul_f32_e32 v108, v108, v116
	v_mul_f32_e32 v112, v104, v112
	v_mul_f32_e32 v107, v107, v115
	v_cvt_pk_bf16_f32 v104, v108, v109
	v_add_u32_e32 v108, 0x110000, v156
	v_mul_f32_e32 v110, v110, v117
	v_mul_f32_e32 v113, v105, v113
	v_mul_f32_e32 v114, v106, v114
	v_cvt_pk_bf16_f32 v105, v110, v111
	v_cvt_pk_bf16_f32 v106, v112, v113
	v_cvt_pk_bf16_f32 v107, v114, v107
	global_store_dwordx4 v108, v[104:107], s[12:13]
	v_cndmask_b32_e64 v111, v100, v92, s[8:9]
	v_mov_b32_e32 v112, 0
	v_add_u32_e32 v104, 0x6000, v157
	s_waitcnt vmcnt(15)
	s_nop 1
	v_mov_b32_e32 v104, v192
	v_mov_b32_e32 v105, v193
	v_mov_b32_e32 v106, v194
	v_mov_b32_e32 v107, v195
	v_cndmask_b32_e64 v110, v101, v93, s[8:9]
	v_mov_b32_dpp v112, v111 quad_perm:[1,0,3,2] row_mask:0xf bank_mask:0xf
	v_mov_b32_e32 v111, 0
	v_cndmask_b32_e64 v115, v96, v88, s[8:9]
	v_mov_b32_e32 v116, 0
	v_cndmask_b32_e64 v109, v102, v94, s[8:9]
	v_mov_b32_dpp v111, v110 quad_perm:[1,0,3,2] row_mask:0xf bank_mask:0xf
	v_mov_b32_e32 v110, 0
	v_cndmask_b32_e64 v114, v97, v89, s[8:9]
	v_mov_b32_dpp v116, v115 quad_perm:[1,0,3,2] row_mask:0xf bank_mask:0xf
	v_mov_b32_e32 v115, 0
	v_cndmask_b32_e64 v108, v103, v95, s[8:9]
	v_mov_b32_dpp v110, v109 quad_perm:[1,0,3,2] row_mask:0xf bank_mask:0xf
	v_mov_b32_e32 v109, 0
	v_cndmask_b32_e64 v113, v98, v90, s[8:9]
	v_mov_b32_dpp v115, v114 quad_perm:[1,0,3,2] row_mask:0xf bank_mask:0xf
	v_mov_b32_e32 v114, 0
	v_mov_b32_dpp v109, v108 quad_perm:[1,0,3,2] row_mask:0xf bank_mask:0xf
	v_cndmask_b32_e64 v108, v99, v91, s[8:9]
	v_mov_b32_dpp v114, v113 quad_perm:[1,0,3,2] row_mask:0xf bank_mask:0xf
	v_mov_b32_e32 v113, 0
	v_cndmask_b32_e64 v101, v111, v101, s[8:9]
	v_cndmask_b32_e64 v103, v109, v103, s[8:9]
	v_mov_b32_dpp v113, v108 quad_perm:[1,0,3,2] row_mask:0xf bank_mask:0xf
	v_cndmask_b32_e64 v97, v115, v97, s[8:9]
	v_cndmask_b32_e64 v96, v116, v96, s[8:9]
	v_cndmask_b32_e64 v100, v112, v100, s[8:9]
	v_cndmask_b32_e64 v99, v113, v99, s[8:9]
	v_cndmask_b32_e64 v102, v110, v102, s[8:9]
	v_cndmask_b32_e64 v98, v114, v98, s[8:9]
	v_add_u32_e32 v117, 0x200000, v156
	v_cndmask_b32_e64 v93, v93, v111, s[8:9]
	v_cndmask_b32_e64 v95, v95, v109, s[8:9]
	v_cndmask_b32_e64 v89, v89, v115, s[8:9]
	v_cndmask_b32_e64 v88, v88, v116, s[8:9]
	v_cndmask_b32_e64 v92, v92, v112, s[8:9]
	v_cndmask_b32_e64 v91, v91, v113, s[8:9]
	v_cndmask_b32_e64 v94, v94, v110, s[8:9]
	v_cndmask_b32_e64 v90, v90, v114, s[8:9]
	v_lshlrev_b32_e32 v108, 16, v104
	v_and_b32_e32 v104, 0xffff0000, v104
	v_fmac_f32_e32 v101, v45, v104
	v_mul_f32_e32 v104, 0x3d372713, v101
;     __device__ __forceinline__ void operator()(const f32x4 (&acc)[2][2][4][2], const Unit& u, int wr, int wc, int fr, int fq, const EpiCtx& X) const {
;     ...
;         EPI_PIECES({ const unsigned uoff = ulo + (unsigned)(rl * UA_LD) * 2u, goff = glo + (unsigned)(rl * 16 * W_SSM) * 2u;
;             S2_ONE(p1a, p1b, uoff, goff); S2_ONE(p2a, p2b, uoff + UA_LD * 2, goff + 16 * W_SSM * 2); })
	v_mul_f32_e32 v104, v101, v104
	v_fma_f32 v104, v101, v104, v101
	v_mul_f32_e32 v104, 0x3f4c422a, v104
	v_lshlrev_b32_e32 v118, 16, v105
	v_and_b32_e32 v105, 0xffff0000, v105
	v_add_f32_e32 v104, v104, v104
	v_fmac_f32_e32 v103, v47, v105
	v_mul_f32_e32 v104, 0xbfb8aa3b, v104
	v_mul_f32_e32 v105, 0x3d372713, v103
	v_exp_f32_e32 v104, v104
	v_mul_f32_e32 v105, v103, v105
	v_fma_f32 v105, v103, v105, v103
	v_mul_f32_e32 v105, 0x3f4c422a, v105
	v_add_f32_e32 v105, v105, v105
	v_add_f32_e32 v104, 1.0, v104
	v_mul_f32_e32 v105, 0xbfb8aa3b, v105
	v_rcp_f32_e32 v104, v104
	v_exp_f32_e32 v105, v105
	v_fmac_f32_e32 v100, v44, v108
	v_mul_f32_e32 v108, 0x3d372713, v100
	v_mul_f32_e32 v101, v101, v104
	v_add_f32_e32 v104, 1.0, v105
	v_lshlrev_b32_e32 v105, 16, v106
	v_and_b32_e32 v106, 0xffff0000, v106
	v_fmac_f32_e32 v96, v40, v105
	v_fmac_f32_e32 v97, v41, v106
	v_mul_f32_e32 v105, 0x3d372713, v96
	v_mul_f32_e32 v106, 0x3d372713, v97
	v_mul_f32_e32 v105, v96, v105
	v_mul_f32_e32 v106, v97, v106
	v_fma_f32 v105, v96, v105, v96
	v_fma_f32 v106, v97, v106, v97
	v_mul_f32_e32 v105, 0x3f4c422a, v105
	v_mul_f32_e32 v106, 0x3f4c422a, v106
	v_add_f32_e32 v105, v105, v105
	v_add_f32_e32 v106, v106, v106
	v_mul_f32_e32 v105, 0xbfb8aa3b, v105
	v_mul_f32_e32 v106, 0xbfb8aa3b, v106
	v_rcp_f32_e32 v104, v104
	v_exp_f32_e32 v105, v105
	v_exp_f32_e32 v106, v106
	v_fmac_f32_e32 v102, v46, v118
	v_mul_f32_e32 v103, v103, v104
	v_add_f32_e32 v104, 1.0, v105
	v_add_f32_e32 v105, 1.0, v106
	v_lshlrev_b32_e32 v106, 16, v107
	v_and_b32_e32 v107, 0xffff0000, v107
	v_fmac_f32_e32 v99, v43, v107
	v_fmac_f32_e32 v98, v42, v106
	v_mul_f32_e32 v107, 0x3d372713, v99
	v_mul_f32_e32 v108, v100, v108
	v_mul_f32_e32 v118, 0x3d372713, v102
	v_mul_f32_e32 v106, 0x3d372713, v98
	v_mul_f32_e32 v107, v99, v107
	v_fma_f32 v108, v100, v108, v100
	v_mul_f32_e32 v118, v102, v118
	v_mul_f32_e32 v106, v98, v106
	v_fma_f32 v107, v99, v107, v99
	v_mul_f32_e32 v108, 0x3f4c422a, v108
	v_fma_f32 v118, v102, v118, v102
	v_fma_f32 v106, v98, v106, v98
	v_mul_f32_e32 v107, 0x3f4c422a, v107
	v_add_f32_e32 v108, v108, v108
	v_mul_f32_e32 v118, 0x3f4c422a, v118
	v_mul_f32_e32 v106, 0x3f4c422a, v106
	v_add_f32_e32 v107, v107, v107
	v_mul_f32_e32 v108, 0xbfb8aa3b, v108
	v_add_f32_e32 v118, v118, v118
	v_add_f32_e32 v106, v106, v106
	v_mul_f32_e32 v107, 0xbfb8aa3b, v107
	v_exp_f32_e32 v108, v108
	v_mul_f32_e32 v118, 0xbfb8aa3b, v118
	v_mul_f32_e32 v106, 0xbfb8aa3b, v106
	v_exp_f32_e32 v107, v107
	v_exp_f32_e32 v118, v118
	v_exp_f32_e32 v106, v106
	v_add_f32_e32 v108, 1.0, v108
	v_add_f32_e32 v107, 1.0, v107
	v_rcp_f32_e32 v108, v108
	v_add_f32_e32 v118, 1.0, v118
	v_rcp_f32_e32 v104, v104
	v_add_f32_e32 v106, 1.0, v106
	v_rcp_f32_e32 v107, v107
	v_rcp_f32_e32 v118, v118
	v_rcp_f32_e32 v105, v105
	v_rcp_f32_e32 v106, v106
	v_mul_f32_e32 v100, v100, v108
	v_mul_f32_e32 v104, v96, v104
	v_mul_f32_e32 v99, v99, v107
	v_cvt_pk_bf16_f32 v96, v100, v101
	v_mul_f32_e32 v102, v102, v118
	v_mul_f32_e32 v105, v97, v105
	v_mul_f32_e32 v106, v98, v106
	v_cvt_pk_bf16_f32 v97, v102, v103
	v_cvt_pk_bf16_f32 v98, v104, v105
	v_cvt_pk_bf16_f32 v99, v106, v99
	global_store_dwordx4 v117, v[96:99], s[12:13]
	s_nop 1
	v_add_u32_e32 v96, 0x6300, v157
	s_waitcnt vmcnt(15)
	s_nop 1
	v_mov_b32_e32 v96, v196
	v_mov_b32_e32 v97, v197
	v_mov_b32_e32 v98, v198
	v_mov_b32_e32 v99, v199
	v_lshlrev_b32_e32 v100, 16, v96
	v_and_b32_e32 v96, 0xffff0000, v96
	v_fmac_f32_e32 v93, v45, v96
	v_mul_f32_e32 v96, 0x3d372713, v93
	v_mul_f32_e32 v96, v93, v96
	v_fma_f32 v96, v93, v96, v93
	v_mul_f32_e32 v96, 0x3f4c422a, v96
	v_lshlrev_b32_e32 v101, 16, v97
	v_and_b32_e32 v97, 0xffff0000, v97
	v_add_f32_e32 v96, v96, v96
	v_fmac_f32_e32 v95, v47, v97
	v_mul_f32_e32 v96, 0xbfb8aa3b, v96
	v_mul_f32_e32 v97, 0x3d372713, v95
	v_exp_f32_e32 v96, v96
	v_mul_f32_e32 v97, v95, v97
	v_fma_f32 v97, v95, v97, v95
	v_mul_f32_e32 v97, 0x3f4c422a, v97
	v_add_f32_e32 v97, v97, v97
	v_add_f32_e32 v96, 1.0, v96
	v_mul_f32_e32 v97, 0xbfb8aa3b, v97
	v_rcp_f32_e32 v96, v96
	v_exp_f32_e32 v97, v97
	v_fmac_f32_e32 v92, v44, v100
	v_mul_f32_e32 v100, 0x3d372713, v92
	v_mul_f32_e32 v93, v93, v96
	v_add_f32_e32 v96, 1.0, v97
	v_lshlrev_b32_e32 v97, 16, v98
	v_and_b32_e32 v98, 0xffff0000, v98
	v_fmac_f32_e32 v88, v40, v97
	v_fmac_f32_e32 v89, v41, v98
	v_mul_f32_e32 v97, 0x3d372713, v88
	v_mul_f32_e32 v98, 0x3d372713, v89
	v_mul_f32_e32 v97, v88, v97
	v_mul_f32_e32 v98, v89, v98
	v_fma_f32 v97, v88, v97, v88
	v_fma_f32 v98, v89, v98, v89
	v_mul_f32_e32 v97, 0x3f4c422a, v97
	v_mul_f32_e32 v98, 0x3f4c422a, v98
	v_add_f32_e32 v97, v97, v97
	v_add_f32_e32 v98, v98, v98
	v_mul_f32_e32 v97, 0xbfb8aa3b, v97
	v_mul_f32_e32 v98, 0xbfb8aa3b, v98
	v_rcp_f32_e32 v96, v96
	v_exp_f32_e32 v97, v97
	v_exp_f32_e32 v98, v98
	v_mul_f32_e32 v100, v92, v100
	v_mul_f32_e32 v95, v95, v96
	v_add_f32_e32 v96, 1.0, v97
	v_add_f32_e32 v97, 1.0, v98
	v_lshlrev_b32_e32 v98, 16, v99
	v_and_b32_e32 v99, 0xffff0000, v99
	v_fmac_f32_e32 v91, v43, v99
	v_fmac_f32_e32 v94, v46, v101
	v_fmac_f32_e32 v90, v42, v98
	v_mul_f32_e32 v99, 0x3d372713, v91
	v_fma_f32 v100, v92, v100, v92
	v_mul_f32_e32 v101, 0x3d372713, v94
	v_mul_f32_e32 v98, 0x3d372713, v90
	v_mul_f32_e32 v99, v91, v99
	v_mul_f32_e32 v100, 0x3f4c422a, v100
	v_mul_f32_e32 v101, v94, v101
	v_mul_f32_e32 v98, v90, v98
	v_fma_f32 v99, v91, v99, v91
	v_add_f32_e32 v100, v100, v100
	v_fma_f32 v101, v94, v101, v94
	v_fma_f32 v98, v90, v98, v90
	v_mul_f32_e32 v99, 0x3f4c422a, v99
	v_mul_f32_e32 v100, 0xbfb8aa3b, v100
	v_mul_f32_e32 v101, 0x3f4c422a, v101
	v_mul_f32_e32 v98, 0x3f4c422a, v98
	v_add_f32_e32 v99, v99, v99
	v_exp_f32_e32 v100, v100
	v_add_f32_e32 v101, v101, v101
	v_add_f32_e32 v98, v98, v98
	v_mul_f32_e32 v99, 0xbfb8aa3b, v99
	v_mul_f32_e32 v101, 0xbfb8aa3b, v101
	v_mul_f32_e32 v98, 0xbfb8aa3b, v98
	v_exp_f32_e32 v99, v99
	v_exp_f32_e32 v101, v101
	v_exp_f32_e32 v98, v98
	v_add_f32_e32 v100, 1.0, v100
	v_rcp_f32_e32 v100, v100
	v_add_f32_e32 v99, 1.0, v99
	v_add_f32_e32 v101, 1.0, v101
	v_rcp_f32_e32 v96, v96
	v_add_f32_e32 v98, 1.0, v98
	v_rcp_f32_e32 v99, v99
	v_rcp_f32_e32 v101, v101
	v_rcp_f32_e32 v97, v97
	v_rcp_f32_e32 v98, v98
	v_mul_f32_e32 v92, v92, v100
	v_mul_f32_e32 v96, v88, v96
	v_mul_f32_e32 v91, v91, v99
	v_cvt_pk_bf16_f32 v88, v92, v93
	v_add_u32_e32 v92, 0x210000, v156
	v_mul_f32_e32 v94, v94, v101
	v_mul_f32_e32 v97, v89, v97
	v_mul_f32_e32 v98, v90, v98
	v_cvt_pk_bf16_f32 v89, v94, v95
	v_cvt_pk_bf16_f32 v90, v96, v97
	v_cvt_pk_bf16_f32 v91, v98, v91
	global_store_dwordx4 v92, v[88:91], s[12:13]
	v_cndmask_b32_e64 v95, v84, v76, s[8:9]
	v_mov_b32_e32 v96, 0
	v_add_u32_e32 v88, 0x9000, v157
	s_waitcnt vmcnt(15)
;     __device__ __forceinline__ void operator()(const f32x4 (&acc)[2][2][4][2], const Unit& u, int wr, int wc, int fr, int fq, const EpiCtx& X) const {
;     ...
;         EPI_PIECES({ const unsigned uoff = ulo + (unsigned)(rl * UA_LD) * 2u, goff = glo + (unsigned)(rl * 16 * W_SSM) * 2u;
;             S2_ONE(p1a, p1b, uoff, goff); S2_ONE(p2a, p2b, uoff + UA_LD * 2, goff + 16 * W_SSM * 2); })
	s_nop 1
	v_mov_b32_e32 v88, v200
	v_mov_b32_e32 v89, v201
	v_mov_b32_e32 v90, v202
	v_mov_b32_e32 v91, v203
	v_cndmask_b32_e64 v94, v85, v77, s[8:9]
	v_mov_b32_dpp v96, v95 quad_perm:[1,0,3,2] row_mask:0xf bank_mask:0xf
	v_mov_b32_e32 v95, 0
	v_cndmask_b32_e64 v99, v80, v72, s[8:9]
	v_mov_b32_e32 v100, 0
	v_cndmask_b32_e64 v93, v86, v78, s[8:9]
	v_mov_b32_dpp v95, v94 quad_perm:[1,0,3,2] row_mask:0xf bank_mask:0xf
	v_mov_b32_e32 v94, 0
	v_cndmask_b32_e64 v98, v81, v73, s[8:9]
	v_mov_b32_dpp v100, v99 quad_perm:[1,0,3,2] row_mask:0xf bank_mask:0xf
	v_mov_b32_e32 v99, 0
	v_cndmask_b32_e64 v92, v87, v79, s[8:9]
	v_mov_b32_dpp v94, v93 quad_perm:[1,0,3,2] row_mask:0xf bank_mask:0xf
	v_mov_b32_e32 v93, 0
	v_cndmask_b32_e64 v97, v82, v74, s[8:9]
	v_mov_b32_dpp v99, v98 quad_perm:[1,0,3,2] row_mask:0xf bank_mask:0xf
	v_mov_b32_e32 v98, 0
	v_mov_b32_dpp v93, v92 quad_perm:[1,0,3,2] row_mask:0xf bank_mask:0xf
	v_cndmask_b32_e64 v92, v83, v75, s[8:9]
	v_mov_b32_dpp v98, v97 quad_perm:[1,0,3,2] row_mask:0xf bank_mask:0xf
	v_mov_b32_e32 v97, 0
	v_cndmask_b32_e64 v85, v95, v85, s[8:9]
	v_cndmask_b32_e64 v87, v93, v87, s[8:9]
	v_mov_b32_dpp v97, v92 quad_perm:[1,0,3,2] row_mask:0xf bank_mask:0xf
	v_cndmask_b32_e64 v81, v99, v81, s[8:9]
	v_cndmask_b32_e64 v80, v100, v80, s[8:9]
	v_cndmask_b32_e64 v84, v96, v84, s[8:9]
	v_cndmask_b32_e64 v83, v97, v83, s[8:9]
	v_cndmask_b32_e64 v86, v94, v86, s[8:9]
	v_cndmask_b32_e64 v82, v98, v82, s[8:9]
	v_add_u32_e32 v101, 0x300000, v156
	v_cndmask_b32_e64 v77, v77, v95, s[8:9]
	v_cndmask_b32_e64 v79, v79, v93, s[8:9]
	v_cndmask_b32_e64 v73, v73, v99, s[8:9]
	v_cndmask_b32_e64 v72, v72, v100, s[8:9]
	v_cndmask_b32_e64 v76, v76, v96, s[8:9]
	v_cndmask_b32_e64 v75, v75, v97, s[8:9]
	v_cndmask_b32_e64 v78, v78, v94, s[8:9]
	v_cndmask_b32_e64 v74, v74, v98, s[8:9]
	v_lshlrev_b32_e32 v92, 16, v88
	v_and_b32_e32 v88, 0xffff0000, v88
	v_fmac_f32_e32 v85, v45, v88
	v_mul_f32_e32 v88, 0x3d372713, v85
	v_mul_f32_e32 v88, v85, v88
	v_fma_f32 v88, v85, v88, v85
	v_mul_f32_e32 v88, 0x3f4c422a, v88
	v_lshlrev_b32_e32 v102, 16, v89
	v_and_b32_e32 v89, 0xffff0000, v89
	v_add_f32_e32 v88, v88, v88
	v_fmac_f32_e32 v87, v47, v89
	v_mul_f32_e32 v88, 0xbfb8aa3b, v88
	v_mul_f32_e32 v89, 0x3d372713, v87
	v_exp_f32_e32 v88, v88
	v_mul_f32_e32 v89, v87, v89
	v_fma_f32 v89, v87, v89, v87
	v_mul_f32_e32 v89, 0x3f4c422a, v89
	v_add_f32_e32 v89, v89, v89
	v_add_f32_e32 v88, 1.0, v88
	v_mul_f32_e32 v89, 0xbfb8aa3b, v89
	v_rcp_f32_e32 v88, v88
	v_exp_f32_e32 v89, v89
	v_fmac_f32_e32 v84, v44, v92
	v_mul_f32_e32 v92, 0x3d372713, v84
	v_mul_f32_e32 v85, v85, v88
	v_add_f32_e32 v88, 1.0, v89
	v_lshlrev_b32_e32 v89, 16, v90
	v_and_b32_e32 v90, 0xffff0000, v90
	v_fmac_f32_e32 v80, v40, v89
	v_fmac_f32_e32 v81, v41, v90
	v_mul_f32_e32 v89, 0x3d372713, v80
	v_mul_f32_e32 v90, 0x3d372713, v81
	v_mul_f32_e32 v89, v80, v89
	v_mul_f32_e32 v90, v81, v90
	v_fma_f32 v89, v80, v89, v80
	v_fma_f32 v90, v81, v90, v81
	v_mul_f32_e32 v89, 0x3f4c422a, v89
	v_mul_f32_e32 v90, 0x3f4c422a, v90
	v_add_f32_e32 v89, v89, v89
	v_add_f32_e32 v90, v90, v90
	v_mul_f32_e32 v89, 0xbfb8aa3b, v89
	v_mul_f32_e32 v90, 0xbfb8aa3b, v90
	v_rcp_f32_e32 v88, v88
	v_exp_f32_e32 v89, v89
	v_exp_f32_e32 v90, v90
	v_fmac_f32_e32 v86, v46, v102
	v_mul_f32_e32 v87, v87, v88
	v_add_f32_e32 v88, 1.0, v89
	v_add_f32_e32 v89, 1.0, v90
	v_lshlrev_b32_e32 v90, 16, v91
	v_and_b32_e32 v91, 0xffff0000, v91
	v_fmac_f32_e32 v83, v43, v91
	v_fmac_f32_e32 v82, v42, v90
	v_mul_f32_e32 v91, 0x3d372713, v83
	v_mul_f32_e32 v92, v84, v92
	v_mul_f32_e32 v102, 0x3d372713, v86
	v_mul_f32_e32 v90, 0x3d372713, v82
	v_mul_f32_e32 v91, v83, v91
	v_fma_f32 v92, v84, v92, v84
	v_mul_f32_e32 v102, v86, v102
	v_mul_f32_e32 v90, v82, v90
	v_fma_f32 v91, v83, v91, v83
	v_mul_f32_e32 v92, 0x3f4c422a, v92
	v_fma_f32 v102, v86, v102, v86
	v_fma_f32 v90, v82, v90, v82
	v_mul_f32_e32 v91, 0x3f4c422a, v91
	v_add_f32_e32 v92, v92, v92
	v_mul_f32_e32 v102, 0x3f4c422a, v102
	v_mul_f32_e32 v90, 0x3f4c422a, v90
	v_add_f32_e32 v91, v91, v91
	v_mul_f32_e32 v92, 0xbfb8aa3b, v92
	v_add_f32_e32 v102, v102, v102
	v_add_f32_e32 v90, v90, v90
	v_mul_f32_e32 v91, 0xbfb8aa3b, v91
	v_exp_f32_e32 v92, v92
	v_mul_f32_e32 v102, 0xbfb8aa3b, v102
	v_mul_f32_e32 v90, 0xbfb8aa3b, v90
	v_exp_f32_e32 v91, v91
	v_exp_f32_e32 v102, v102
	v_exp_f32_e32 v90, v90
	v_add_f32_e32 v92, 1.0, v92
	v_add_f32_e32 v91, 1.0, v91
	v_rcp_f32_e32 v92, v92
	v_add_f32_e32 v102, 1.0, v102
	v_rcp_f32_e32 v88, v88
	v_add_f32_e32 v90, 1.0, v90
	v_rcp_f32_e32 v91, v91
	v_rcp_f32_e32 v102, v102
	v_rcp_f32_e32 v89, v89
	v_rcp_f32_e32 v90, v90
	v_mul_f32_e32 v84, v84, v92
	v_mul_f32_e32 v88, v80, v88
	v_mul_f32_e32 v83, v83, v91
	v_cvt_pk_bf16_f32 v80, v84, v85
	v_mul_f32_e32 v86, v86, v102
	v_mul_f32_e32 v89, v81, v89
	v_mul_f32_e32 v90, v82, v90
	v_cvt_pk_bf16_f32 v81, v86, v87
	v_cvt_pk_bf16_f32 v82, v88, v89
	v_cvt_pk_bf16_f32 v83, v90, v83
	global_store_dwordx4 v101, v[80:83], s[12:13]
	s_nop 1
	v_add_u32_e32 v80, 0x9300, v157
	s_waitcnt vmcnt(15)
;     __device__ __forceinline__ void operator()(const f32x4 (&acc)[2][2][4][2], const Unit& u, int wr, int wc, int fr, int fq, const EpiCtx& X) const {
;     ...
;         EPI_PIECES({ const unsigned uoff = ulo + (unsigned)(rl * UA_LD) * 2u, goff = glo + (unsigned)(rl * 16 * W_SSM) * 2u;
;             S2_ONE(p1a, p1b, uoff, goff); S2_ONE(p2a, p2b, uoff + UA_LD * 2, goff + 16 * W_SSM * 2); })
	s_nop 1
	v_mov_b32_e32 v80, v204
	v_mov_b32_e32 v81, v205
	v_mov_b32_e32 v82, v206
	v_mov_b32_e32 v83, v207
	v_lshlrev_b32_e32 v84, 16, v80
	v_and_b32_e32 v80, 0xffff0000, v80
	v_fmac_f32_e32 v77, v45, v80
	v_mul_f32_e32 v80, 0x3d372713, v77
	v_mul_f32_e32 v80, v77, v80
	v_fma_f32 v80, v77, v80, v77
	v_mul_f32_e32 v80, 0x3f4c422a, v80
	v_lshlrev_b32_e32 v85, 16, v81
	v_and_b32_e32 v81, 0xffff0000, v81
	v_add_f32_e32 v80, v80, v80
	v_fmac_f32_e32 v79, v47, v81
	v_mul_f32_e32 v80, 0xbfb8aa3b, v80
	v_mul_f32_e32 v81, 0x3d372713, v79
	v_exp_f32_e32 v80, v80
	v_mul_f32_e32 v81, v79, v81
	v_fma_f32 v81, v79, v81, v79
	v_mul_f32_e32 v81, 0x3f4c422a, v81
	v_add_f32_e32 v81, v81, v81
	v_add_f32_e32 v80, 1.0, v80
	v_mul_f32_e32 v81, 0xbfb8aa3b, v81
	v_rcp_f32_e32 v80, v80
	v_exp_f32_e32 v81, v81
	v_fmac_f32_e32 v76, v44, v84
	v_mul_f32_e32 v84, 0x3d372713, v76
	v_mul_f32_e32 v77, v77, v80
	v_add_f32_e32 v80, 1.0, v81
	v_lshlrev_b32_e32 v81, 16, v82
	v_and_b32_e32 v82, 0xffff0000, v82
	v_fmac_f32_e32 v72, v40, v81
	v_fmac_f32_e32 v73, v41, v82
	v_mul_f32_e32 v81, 0x3d372713, v72
	v_mul_f32_e32 v82, 0x3d372713, v73
	v_mul_f32_e32 v81, v72, v81
	v_mul_f32_e32 v82, v73, v82
	v_fma_f32 v81, v72, v81, v72
	v_fma_f32 v82, v73, v82, v73
	v_mul_f32_e32 v81, 0x3f4c422a, v81
	v_mul_f32_e32 v82, 0x3f4c422a, v82
	v_add_f32_e32 v81, v81, v81
	v_add_f32_e32 v82, v82, v82
	v_mul_f32_e32 v81, 0xbfb8aa3b, v81
	v_mul_f32_e32 v82, 0xbfb8aa3b, v82
	v_rcp_f32_e32 v80, v80
	v_exp_f32_e32 v81, v81
	v_exp_f32_e32 v82, v82
	v_mul_f32_e32 v84, v76, v84
	v_mul_f32_e32 v79, v79, v80
	v_add_f32_e32 v80, 1.0, v81
	v_add_f32_e32 v81, 1.0, v82
	v_lshlrev_b32_e32 v82, 16, v83
	v_and_b32_e32 v83, 0xffff0000, v83
	v_fmac_f32_e32 v75, v43, v83
	v_fmac_f32_e32 v78, v46, v85
	v_fmac_f32_e32 v74, v42, v82
	v_mul_f32_e32 v83, 0x3d372713, v75
	v_fma_f32 v84, v76, v84, v76
	v_mul_f32_e32 v85, 0x3d372713, v78
	v_mul_f32_e32 v82, 0x3d372713, v74
	v_mul_f32_e32 v83, v75, v83
	v_mul_f32_e32 v84, 0x3f4c422a, v84
	v_mul_f32_e32 v85, v78, v85
	v_mul_f32_e32 v82, v74, v82
	v_fma_f32 v83, v75, v83, v75
	v_add_f32_e32 v84, v84, v84
	v_fma_f32 v85, v78, v85, v78
	v_fma_f32 v82, v74, v82, v74
	v_mul_f32_e32 v83, 0x3f4c422a, v83
	v_mul_f32_e32 v84, 0xbfb8aa3b, v84
	v_mul_f32_e32 v85, 0x3f4c422a, v85
	v_mul_f32_e32 v82, 0x3f4c422a, v82
	v_add_f32_e32 v83, v83, v83
	v_exp_f32_e32 v84, v84
	v_add_f32_e32 v85, v85, v85
	v_add_f32_e32 v82, v82, v82
	v_mul_f32_e32 v83, 0xbfb8aa3b, v83
	v_mul_f32_e32 v85, 0xbfb8aa3b, v85
	v_mul_f32_e32 v82, 0xbfb8aa3b, v82
	v_exp_f32_e32 v83, v83
	v_exp_f32_e32 v85, v85
	v_exp_f32_e32 v82, v82
	v_add_f32_e32 v84, 1.0, v84
	v_rcp_f32_e32 v84, v84
	v_add_f32_e32 v83, 1.0, v83
	v_add_f32_e32 v85, 1.0, v85
	v_rcp_f32_e32 v80, v80
	v_add_f32_e32 v82, 1.0, v82
	v_rcp_f32_e32 v83, v83
	v_rcp_f32_e32 v85, v85
	v_rcp_f32_e32 v81, v81
	v_rcp_f32_e32 v82, v82
	v_mul_f32_e32 v76, v76, v84
	v_mul_f32_e32 v80, v72, v80
	v_mul_f32_e32 v75, v75, v83
	v_cvt_pk_bf16_f32 v72, v76, v77
	v_add_u32_e32 v76, 0x310000, v156
	v_mul_f32_e32 v78, v78, v85
	v_mul_f32_e32 v81, v73, v81
	v_mul_f32_e32 v82, v74, v82
	v_cvt_pk_bf16_f32 v73, v78, v79
	v_cvt_pk_bf16_f32 v74, v80, v81
	v_cvt_pk_bf16_f32 v75, v82, v75
	global_store_dwordx4 v76, v[72:75], s[12:13]
	v_cndmask_b32_e64 v79, v68, v60, s[8:9]
	v_mov_b32_e32 v80, 0
	v_add_u32_e32 v72, 0x18000, v157
	s_waitcnt vmcnt(15)
	s_nop 1
	v_mov_b32_e32 v72, v208
	v_mov_b32_e32 v73, v209
	v_mov_b32_e32 v74, v210
	v_mov_b32_e32 v75, v211
	v_cndmask_b32_e64 v78, v69, v61, s[8:9]
	v_mov_b32_dpp v80, v79 quad_perm:[1,0,3,2] row_mask:0xf bank_mask:0xf
	v_mov_b32_e32 v79, 0
	v_cndmask_b32_e64 v83, v64, v56, s[8:9]
	v_mov_b32_e32 v84, 0
	v_cndmask_b32_e64 v77, v70, v62, s[8:9]
	v_mov_b32_dpp v79, v78 quad_perm:[1,0,3,2] row_mask:0xf bank_mask:0xf
	v_mov_b32_e32 v78, 0
	v_cndmask_b32_e64 v82, v65, v57, s[8:9]
	v_mov_b32_dpp v84, v83 quad_perm:[1,0,3,2] row_mask:0xf bank_mask:0xf
	v_mov_b32_e32 v83, 0
	v_cndmask_b32_e64 v76, v71, v63, s[8:9]
	v_mov_b32_dpp v78, v77 quad_perm:[1,0,3,2] row_mask:0xf bank_mask:0xf
	v_mov_b32_e32 v77, 0
	v_cndmask_b32_e64 v81, v66, v58, s[8:9]
	v_mov_b32_dpp v83, v82 quad_perm:[1,0,3,2] row_mask:0xf bank_mask:0xf
	v_mov_b32_e32 v82, 0
	v_mov_b32_dpp v77, v76 quad_perm:[1,0,3,2] row_mask:0xf bank_mask:0xf
	v_cndmask_b32_e64 v76, v67, v59, s[8:9]
	v_mov_b32_dpp v82, v81 quad_perm:[1,0,3,2] row_mask:0xf bank_mask:0xf
	v_mov_b32_e32 v81, 0
	v_cndmask_b32_e64 v69, v79, v69, s[8:9]
	v_cndmask_b32_e64 v71, v77, v71, s[8:9]
	v_mov_b32_dpp v81, v76 quad_perm:[1,0,3,2] row_mask:0xf bank_mask:0xf
	v_cndmask_b32_e64 v65, v83, v65, s[8:9]
	v_cndmask_b32_e64 v64, v84, v64, s[8:9]
	v_cndmask_b32_e64 v68, v80, v68, s[8:9]
	v_cndmask_b32_e64 v67, v81, v67, s[8:9]
	v_cndmask_b32_e64 v70, v78, v70, s[8:9]
	v_cndmask_b32_e64 v66, v82, v66, s[8:9]
	v_add_u32_e32 v85, 0x800000, v156
	v_cndmask_b32_e64 v61, v61, v79, s[8:9]
	v_cndmask_b32_e64 v63, v63, v77, s[8:9]
	v_cndmask_b32_e64 v57, v57, v83, s[8:9]
	v_cndmask_b32_e64 v56, v56, v84, s[8:9]
	v_cndmask_b32_e64 v60, v60, v80, s[8:9]
	v_cndmask_b32_e64 v59, v59, v81, s[8:9]
	v_cndmask_b32_e64 v62, v62, v78, s[8:9]
	v_cndmask_b32_e64 v58, v58, v82, s[8:9]
	v_lshlrev_b32_e32 v76, 16, v72
	v_and_b32_e32 v72, 0xffff0000, v72
	v_fmac_f32_e32 v69, v45, v72
	v_mul_f32_e32 v72, 0x3d372713, v69
	v_mul_f32_e32 v72, v69, v72
	v_fma_f32 v72, v69, v72, v69
	v_mul_f32_e32 v72, 0x3f4c422a, v72
	v_lshlrev_b32_e32 v86, 16, v73
	v_and_b32_e32 v73, 0xffff0000, v73
	v_add_f32_e32 v72, v72, v72
	v_fmac_f32_e32 v71, v47, v73
	v_mul_f32_e32 v72, 0xbfb8aa3b, v72
	v_mul_f32_e32 v73, 0x3d372713, v71
	v_exp_f32_e32 v72, v72
; __device__ __forceinline__ float fast_sigmoid(float x) { return __builtin_amdgcn_rcpf(1.0f + fast_exp(-x)); }
; __device__ __forceinline__ float gelu_tanh(float x) {
;     const float a = 0.7978845608028654f * (x + 0.044715f * x * x * x);
;     return x * fast_sigmoid(2.0f * a);
; }
;     __device__ __forceinline__ void operator()(const f32x4 (&acc)[2][2][4][2], const Unit& u, int wr, int wc, int fr, int fq, const EpiCtx& X) const {
;     ...
;         EPI_PIECES({ const unsigned uoff = ulo + (unsigned)(rl * UA_LD) * 2u, goff = glo + (unsigned)(rl * 16 * W_SSM) * 2u;
;             S2_ONE(p1a, p1b, uoff, goff); S2_ONE(p2a, p2b, uoff + UA_LD * 2, goff + 16 * W_SSM * 2); })
	v_mul_f32_e32 v73, v71, v73
	v_fma_f32 v73, v71, v73, v71
	v_mul_f32_e32 v73, 0x3f4c422a, v73
	v_add_f32_e32 v73, v73, v73
	v_add_f32_e32 v72, 1.0, v72
	v_mul_f32_e32 v73, 0xbfb8aa3b, v73
	v_rcp_f32_e32 v72, v72
	v_exp_f32_e32 v73, v73
	v_fmac_f32_e32 v68, v44, v76
	v_mul_f32_e32 v76, 0x3d372713, v68
	v_mul_f32_e32 v69, v69, v72
	v_add_f32_e32 v72, 1.0, v73
	v_lshlrev_b32_e32 v73, 16, v74
	v_and_b32_e32 v74, 0xffff0000, v74
	v_fmac_f32_e32 v64, v40, v73
	v_fmac_f32_e32 v65, v41, v74
	v_mul_f32_e32 v73, 0x3d372713, v64
	v_mul_f32_e32 v74, 0x3d372713, v65
	v_mul_f32_e32 v73, v64, v73
	v_mul_f32_e32 v74, v65, v74
	v_fma_f32 v73, v64, v73, v64
	v_fma_f32 v74, v65, v74, v65
	v_mul_f32_e32 v73, 0x3f4c422a, v73
	v_mul_f32_e32 v74, 0x3f4c422a, v74
	v_add_f32_e32 v73, v73, v73
	v_add_f32_e32 v74, v74, v74
	v_mul_f32_e32 v73, 0xbfb8aa3b, v73
	v_mul_f32_e32 v74, 0xbfb8aa3b, v74
	v_rcp_f32_e32 v72, v72
	v_exp_f32_e32 v73, v73
	v_exp_f32_e32 v74, v74
	v_fmac_f32_e32 v70, v46, v86
	v_mul_f32_e32 v71, v71, v72
	v_add_f32_e32 v72, 1.0, v73
	v_add_f32_e32 v73, 1.0, v74
	v_lshlrev_b32_e32 v74, 16, v75
	v_and_b32_e32 v75, 0xffff0000, v75
	v_fmac_f32_e32 v67, v43, v75
	v_fmac_f32_e32 v66, v42, v74
	v_mul_f32_e32 v75, 0x3d372713, v67
	v_mul_f32_e32 v76, v68, v76
	v_mul_f32_e32 v86, 0x3d372713, v70
	v_mul_f32_e32 v74, 0x3d372713, v66
	v_mul_f32_e32 v75, v67, v75
	v_fma_f32 v76, v68, v76, v68
	v_mul_f32_e32 v86, v70, v86
	v_mul_f32_e32 v74, v66, v74
	v_fma_f32 v75, v67, v75, v67
	v_mul_f32_e32 v76, 0x3f4c422a, v76
	v_fma_f32 v86, v70, v86, v70
	v_fma_f32 v74, v66, v74, v66
	v_mul_f32_e32 v75, 0x3f4c422a, v75
	v_add_f32_e32 v76, v76, v76
	v_mul_f32_e32 v86, 0x3f4c422a, v86
	v_mul_f32_e32 v74, 0x3f4c422a, v74
	v_add_f32_e32 v75, v75, v75
	v_mul_f32_e32 v76, 0xbfb8aa3b, v76
	v_add_f32_e32 v86, v86, v86
	v_add_f32_e32 v74, v74, v74
	v_mul_f32_e32 v75, 0xbfb8aa3b, v75
	v_exp_f32_e32 v76, v76
	v_mul_f32_e32 v86, 0xbfb8aa3b, v86
	v_mul_f32_e32 v74, 0xbfb8aa3b, v74
	v_exp_f32_e32 v75, v75
	v_exp_f32_e32 v86, v86
	v_exp_f32_e32 v74, v74
	v_add_f32_e32 v76, 1.0, v76
	v_add_f32_e32 v75, 1.0, v75
	v_rcp_f32_e32 v76, v76
	v_add_f32_e32 v86, 1.0, v86
	v_rcp_f32_e32 v72, v72
	v_add_f32_e32 v74, 1.0, v74
	v_rcp_f32_e32 v75, v75
	v_rcp_f32_e32 v86, v86
	v_rcp_f32_e32 v73, v73
	v_rcp_f32_e32 v74, v74
	v_mul_f32_e32 v68, v68, v76
	v_mul_f32_e32 v72, v64, v72
	v_mul_f32_e32 v67, v67, v75
	v_cvt_pk_bf16_f32 v64, v68, v69
	v_mul_f32_e32 v70, v70, v86
	v_mul_f32_e32 v73, v65, v73
	v_mul_f32_e32 v74, v66, v74
	v_cvt_pk_bf16_f32 v65, v70, v71
	v_cvt_pk_bf16_f32 v66, v72, v73
	v_cvt_pk_bf16_f32 v67, v74, v67
	global_store_dwordx4 v85, v[64:67], s[12:13]
	s_nop 1
	v_add_u32_e32 v64, 0x18300, v157
	s_waitcnt vmcnt(15)
	s_nop 1
	v_mov_b32_e32 v64, v220
	v_mov_b32_e32 v65, v221
	v_mov_b32_e32 v66, v222
	v_mov_b32_e32 v67, v223
	v_lshlrev_b32_e32 v68, 16, v64
	v_and_b32_e32 v64, 0xffff0000, v64
	v_fmac_f32_e32 v61, v45, v64
	v_mul_f32_e32 v64, 0x3d372713, v61
	v_mul_f32_e32 v64, v61, v64
	v_fma_f32 v64, v61, v64, v61
	v_mul_f32_e32 v64, 0x3f4c422a, v64
	v_lshlrev_b32_e32 v69, 16, v65
	v_and_b32_e32 v65, 0xffff0000, v65
	v_add_f32_e32 v64, v64, v64
	v_fmac_f32_e32 v63, v47, v65
	v_mul_f32_e32 v64, 0xbfb8aa3b, v64
	v_mul_f32_e32 v65, 0x3d372713, v63
	v_exp_f32_e32 v64, v64
	v_mul_f32_e32 v65, v63, v65
	v_fma_f32 v65, v63, v65, v63
	v_mul_f32_e32 v65, 0x3f4c422a, v65
	v_add_f32_e32 v65, v65, v65
	v_add_f32_e32 v64, 1.0, v64
	v_mul_f32_e32 v65, 0xbfb8aa3b, v65
	v_rcp_f32_e32 v64, v64
	v_exp_f32_e32 v65, v65
	v_fmac_f32_e32 v60, v44, v68
	v_mul_f32_e32 v68, 0x3d372713, v60
	v_mul_f32_e32 v61, v61, v64
	v_add_f32_e32 v64, 1.0, v65
	v_lshlrev_b32_e32 v65, 16, v66
	v_and_b32_e32 v66, 0xffff0000, v66
	v_fmac_f32_e32 v56, v40, v65
	v_fmac_f32_e32 v57, v41, v66
	v_mul_f32_e32 v65, 0x3d372713, v56
	v_mul_f32_e32 v66, 0x3d372713, v57
	v_mul_f32_e32 v65, v56, v65
	v_mul_f32_e32 v66, v57, v66
	v_fma_f32 v65, v56, v65, v56
	v_fma_f32 v66, v57, v66, v57
	v_mul_f32_e32 v65, 0x3f4c422a, v65
	v_mul_f32_e32 v66, 0x3f4c422a, v66
	v_add_f32_e32 v65, v65, v65
	v_add_f32_e32 v66, v66, v66
	v_mul_f32_e32 v65, 0xbfb8aa3b, v65
	v_mul_f32_e32 v66, 0xbfb8aa3b, v66
	v_rcp_f32_e32 v64, v64
	v_exp_f32_e32 v65, v65
	v_exp_f32_e32 v66, v66
	v_mul_f32_e32 v68, v60, v68
	v_mul_f32_e32 v63, v63, v64
	v_add_f32_e32 v64, 1.0, v65
	v_add_f32_e32 v65, 1.0, v66
	v_lshlrev_b32_e32 v66, 16, v67
	v_and_b32_e32 v67, 0xffff0000, v67
	v_fmac_f32_e32 v59, v43, v67
	v_fmac_f32_e32 v62, v46, v69
	v_fmac_f32_e32 v58, v42, v66
	v_mul_f32_e32 v67, 0x3d372713, v59
	v_fma_f32 v68, v60, v68, v60
	v_mul_f32_e32 v69, 0x3d372713, v62
	v_mul_f32_e32 v66, 0x3d372713, v58
	v_mul_f32_e32 v67, v59, v67
	v_mul_f32_e32 v68, 0x3f4c422a, v68
	v_mul_f32_e32 v69, v62, v69
	v_mul_f32_e32 v66, v58, v66
	v_fma_f32 v67, v59, v67, v59
	v_add_f32_e32 v68, v68, v68
	v_fma_f32 v69, v62, v69, v62
	v_fma_f32 v66, v58, v66, v58
	v_mul_f32_e32 v67, 0x3f4c422a, v67
	v_mul_f32_e32 v68, 0xbfb8aa3b, v68
	v_mul_f32_e32 v69, 0x3f4c422a, v69
	v_mul_f32_e32 v66, 0x3f4c422a, v66
	v_add_f32_e32 v67, v67, v67
	v_exp_f32_e32 v68, v68
	v_add_f32_e32 v69, v69, v69
	v_add_f32_e32 v66, v66, v66
	v_mul_f32_e32 v67, 0xbfb8aa3b, v67
	v_mul_f32_e32 v69, 0xbfb8aa3b, v69
	v_mul_f32_e32 v66, 0xbfb8aa3b, v66
	v_exp_f32_e32 v67, v67
	v_exp_f32_e32 v69, v69
	v_exp_f32_e32 v66, v66
	v_add_f32_e32 v68, 1.0, v68
	v_rcp_f32_e32 v68, v68
	v_add_f32_e32 v67, 1.0, v67
	v_add_f32_e32 v69, 1.0, v69
	v_rcp_f32_e32 v64, v64
	v_add_f32_e32 v66, 1.0, v66
	v_rcp_f32_e32 v67, v67
	v_rcp_f32_e32 v69, v69
	v_rcp_f32_e32 v65, v65
	v_rcp_f32_e32 v66, v66
	v_mul_f32_e32 v60, v60, v68
	v_mul_f32_e32 v64, v56, v64
	v_mul_f32_e32 v59, v59, v67
	v_cvt_pk_bf16_f32 v56, v60, v61
	v_add_u32_e32 v60, 0x810000, v156
	v_mul_f32_e32 v62, v62, v69
	v_mul_f32_e32 v65, v57, v65
	v_mul_f32_e32 v66, v58, v66
	v_cvt_pk_bf16_f32 v57, v62, v63
	v_cvt_pk_bf16_f32 v58, v64, v65
	v_cvt_pk_bf16_f32 v59, v66, v59
	global_store_dwordx4 v60, v[56:59], s[12:13]
	v_cndmask_b32_e64 v63, v52, v36, s[8:9]
	v_mov_b32_e32 v64, 0
	v_add_u32_e32 v56, 0x1b000, v157
	s_waitcnt vmcnt(15)
;     __device__ __forceinline__ void operator()(const f32x4 (&acc)[2][2][4][2], const Unit& u, int wr, int wc, int fr, int fq, const EpiCtx& X) const {
;     ...
;         EPI_PIECES({ const unsigned uoff = ulo + (unsigned)(rl * UA_LD) * 2u, goff = glo + (unsigned)(rl * 16 * W_SSM) * 2u;
;             S2_ONE(p1a, p1b, uoff, goff); S2_ONE(p2a, p2b, uoff + UA_LD * 2, goff + 16 * W_SSM * 2); })
	s_nop 1
	v_mov_b32_e32 v56, v224
	v_mov_b32_e32 v57, v225
	v_mov_b32_e32 v58, v226
	v_mov_b32_e32 v59, v227
	v_cndmask_b32_e64 v62, v53, v37, s[8:9]
	v_mov_b32_dpp v64, v63 quad_perm:[1,0,3,2] row_mask:0xf bank_mask:0xf
	v_mov_b32_e32 v63, 0
	v_cndmask_b32_e64 v67, v48, v32, s[8:9]
	v_mov_b32_e32 v68, 0
	v_cndmask_b32_e64 v61, v54, v38, s[8:9]
	v_mov_b32_dpp v63, v62 quad_perm:[1,0,3,2] row_mask:0xf bank_mask:0xf
	v_mov_b32_e32 v62, 0
	v_cndmask_b32_e64 v66, v49, v33, s[8:9]
	v_mov_b32_dpp v68, v67 quad_perm:[1,0,3,2] row_mask:0xf bank_mask:0xf
	v_mov_b32_e32 v67, 0
	v_cndmask_b32_e64 v60, v55, v39, s[8:9]
	v_mov_b32_dpp v62, v61 quad_perm:[1,0,3,2] row_mask:0xf bank_mask:0xf
	v_mov_b32_e32 v61, 0
	v_cndmask_b32_e64 v65, v50, v34, s[8:9]
	v_mov_b32_dpp v67, v66 quad_perm:[1,0,3,2] row_mask:0xf bank_mask:0xf
	v_mov_b32_e32 v66, 0
	v_mov_b32_dpp v61, v60 quad_perm:[1,0,3,2] row_mask:0xf bank_mask:0xf
	v_cndmask_b32_e64 v60, v51, v35, s[8:9]
	v_mov_b32_dpp v66, v65 quad_perm:[1,0,3,2] row_mask:0xf bank_mask:0xf
	v_mov_b32_e32 v65, 0
	v_cndmask_b32_e64 v53, v63, v53, s[8:9]
	v_cndmask_b32_e64 v55, v61, v55, s[8:9]
	v_mov_b32_dpp v65, v60 quad_perm:[1,0,3,2] row_mask:0xf bank_mask:0xf
	v_cndmask_b32_e64 v49, v67, v49, s[8:9]
	v_cndmask_b32_e64 v48, v68, v48, s[8:9]
	v_cndmask_b32_e64 v52, v64, v52, s[8:9]
	v_cndmask_b32_e64 v51, v65, v51, s[8:9]
	v_cndmask_b32_e64 v54, v62, v54, s[8:9]
	v_cndmask_b32_e64 v50, v66, v50, s[8:9]
	v_add_u32_e32 v69, 0x900000, v156
	v_cndmask_b32_e64 v37, v37, v63, s[8:9]
	v_cndmask_b32_e64 v39, v39, v61, s[8:9]
	v_cndmask_b32_e64 v33, v33, v67, s[8:9]
	v_cndmask_b32_e64 v32, v32, v68, s[8:9]
	v_cndmask_b32_e64 v36, v36, v64, s[8:9]
	v_cndmask_b32_e64 v35, v35, v65, s[8:9]
	v_cndmask_b32_e64 v38, v38, v62, s[8:9]
	v_cndmask_b32_e64 v34, v34, v66, s[8:9]
	v_lshlrev_b32_e32 v60, 16, v56
	v_and_b32_e32 v56, 0xffff0000, v56
	v_fmac_f32_e32 v53, v45, v56
	v_mul_f32_e32 v56, 0x3d372713, v53
	v_mul_f32_e32 v56, v53, v56
	v_fma_f32 v56, v53, v56, v53
	v_mul_f32_e32 v56, 0x3f4c422a, v56
	v_lshlrev_b32_e32 v70, 16, v57
	v_and_b32_e32 v57, 0xffff0000, v57
	v_add_f32_e32 v56, v56, v56
	v_fmac_f32_e32 v55, v47, v57
	v_mul_f32_e32 v56, 0xbfb8aa3b, v56
	v_mul_f32_e32 v57, 0x3d372713, v55
	v_exp_f32_e32 v56, v56
	v_mul_f32_e32 v57, v55, v57
	v_fma_f32 v57, v55, v57, v55
	v_mul_f32_e32 v57, 0x3f4c422a, v57
	v_add_f32_e32 v57, v57, v57
	v_add_f32_e32 v56, 1.0, v56
	v_mul_f32_e32 v57, 0xbfb8aa3b, v57
	v_rcp_f32_e32 v56, v56
	v_exp_f32_e32 v57, v57
	v_fmac_f32_e32 v52, v44, v60
	v_mul_f32_e32 v60, 0x3d372713, v52
	v_mul_f32_e32 v53, v53, v56
	v_add_f32_e32 v56, 1.0, v57
	v_lshlrev_b32_e32 v57, 16, v58
	v_and_b32_e32 v58, 0xffff0000, v58
	v_fmac_f32_e32 v48, v40, v57
	v_fmac_f32_e32 v49, v41, v58
	v_mul_f32_e32 v57, 0x3d372713, v48
	v_mul_f32_e32 v58, 0x3d372713, v49
	v_mul_f32_e32 v57, v48, v57
	v_mul_f32_e32 v58, v49, v58
	v_fma_f32 v57, v48, v57, v48
	v_fma_f32 v58, v49, v58, v49
	v_mul_f32_e32 v57, 0x3f4c422a, v57
	v_mul_f32_e32 v58, 0x3f4c422a, v58
	v_add_f32_e32 v57, v57, v57
	v_add_f32_e32 v58, v58, v58
	v_mul_f32_e32 v57, 0xbfb8aa3b, v57
	v_mul_f32_e32 v58, 0xbfb8aa3b, v58
	v_rcp_f32_e32 v56, v56
	v_exp_f32_e32 v57, v57
	v_exp_f32_e32 v58, v58
	v_fmac_f32_e32 v54, v46, v70
	v_mul_f32_e32 v55, v55, v56
	v_add_f32_e32 v56, 1.0, v57
	v_add_f32_e32 v57, 1.0, v58
	v_lshlrev_b32_e32 v58, 16, v59
	v_and_b32_e32 v59, 0xffff0000, v59
	v_fmac_f32_e32 v51, v43, v59
	v_fmac_f32_e32 v50, v42, v58
	v_mul_f32_e32 v59, 0x3d372713, v51
	v_mul_f32_e32 v60, v52, v60
	v_mul_f32_e32 v70, 0x3d372713, v54
	v_mul_f32_e32 v58, 0x3d372713, v50
	v_mul_f32_e32 v59, v51, v59
	v_fma_f32 v60, v52, v60, v52
	v_mul_f32_e32 v70, v54, v70
	v_mul_f32_e32 v58, v50, v58
	v_fma_f32 v59, v51, v59, v51
	v_mul_f32_e32 v60, 0x3f4c422a, v60
	v_fma_f32 v70, v54, v70, v54
	v_fma_f32 v58, v50, v58, v50
	v_mul_f32_e32 v59, 0x3f4c422a, v59
	v_add_f32_e32 v60, v60, v60
	v_mul_f32_e32 v70, 0x3f4c422a, v70
	v_mul_f32_e32 v58, 0x3f4c422a, v58
	v_add_f32_e32 v59, v59, v59
	v_mul_f32_e32 v60, 0xbfb8aa3b, v60
	v_add_f32_e32 v70, v70, v70
	v_add_f32_e32 v58, v58, v58
	v_mul_f32_e32 v59, 0xbfb8aa3b, v59
	v_exp_f32_e32 v60, v60
	v_mul_f32_e32 v70, 0xbfb8aa3b, v70
	v_mul_f32_e32 v58, 0xbfb8aa3b, v58
	v_exp_f32_e32 v59, v59
	v_exp_f32_e32 v70, v70
	v_exp_f32_e32 v58, v58
	v_add_f32_e32 v60, 1.0, v60
	v_add_f32_e32 v59, 1.0, v59
	v_rcp_f32_e32 v60, v60
	v_add_f32_e32 v70, 1.0, v70
	v_rcp_f32_e32 v56, v56
	v_add_f32_e32 v58, 1.0, v58
	v_rcp_f32_e32 v59, v59
	v_rcp_f32_e32 v70, v70
	v_rcp_f32_e32 v57, v57
	v_rcp_f32_e32 v58, v58
	v_mul_f32_e32 v52, v52, v60
	v_mul_f32_e32 v56, v48, v56
	v_mul_f32_e32 v51, v51, v59
	v_cvt_pk_bf16_f32 v48, v52, v53
	v_mul_f32_e32 v54, v54, v70
	v_mul_f32_e32 v57, v49, v57
	v_mul_f32_e32 v58, v50, v58
	v_cvt_pk_bf16_f32 v49, v54, v55
	v_cvt_pk_bf16_f32 v50, v56, v57
	v_cvt_pk_bf16_f32 v51, v58, v51
	global_store_dwordx4 v69, v[48:51], s[12:13]
	s_nop 1
	v_add_u32_e32 v48, 0x1b300, v157
	s_waitcnt vmcnt(15)
;     __device__ __forceinline__ void operator()(const f32x4 (&acc)[2][2][4][2], const Unit& u, int wr, int wc, int fr, int fq, const EpiCtx& X) const {
;     ...
;         EPI_PIECES({ const unsigned uoff = ulo + (unsigned)(rl * UA_LD) * 2u, goff = glo + (unsigned)(rl * 16 * W_SSM) * 2u;
;             S2_ONE(p1a, p1b, uoff, goff); S2_ONE(p2a, p2b, uoff + UA_LD * 2, goff + 16 * W_SSM * 2); })
	s_nop 1
	v_mov_b32_e32 v48, v228
	v_mov_b32_e32 v49, v229
	v_mov_b32_e32 v50, v230
	v_mov_b32_e32 v51, v231
	v_lshlrev_b32_e32 v52, 16, v48
	v_and_b32_e32 v48, 0xffff0000, v48
	v_fmac_f32_e32 v37, v45, v48
	v_mul_f32_e32 v48, 0x3d372713, v37
	v_mul_f32_e32 v48, v37, v48
	v_fma_f32 v48, v37, v48, v37
	v_mul_f32_e32 v48, 0x3f4c422a, v48
	v_lshlrev_b32_e32 v53, 16, v49
	v_and_b32_e32 v49, 0xffff0000, v49
	v_add_f32_e32 v48, v48, v48
	v_fmac_f32_e32 v39, v47, v49
	v_mul_f32_e32 v48, 0xbfb8aa3b, v48
	v_mul_f32_e32 v49, 0x3d372713, v39
	v_exp_f32_e32 v48, v48
	v_mul_f32_e32 v49, v39, v49
	v_fma_f32 v49, v39, v49, v39
	v_mul_f32_e32 v49, 0x3f4c422a, v49
	v_add_f32_e32 v49, v49, v49
	v_add_f32_e32 v48, 1.0, v48
	v_mul_f32_e32 v49, 0xbfb8aa3b, v49
	v_rcp_f32_e32 v48, v48
	v_exp_f32_e32 v49, v49
	v_fmac_f32_e32 v36, v44, v52
	v_mul_f32_e32 v52, 0x3d372713, v36
	v_mul_f32_e32 v37, v37, v48
	v_add_f32_e32 v48, 1.0, v49
	v_lshlrev_b32_e32 v49, 16, v50
	v_and_b32_e32 v50, 0xffff0000, v50
	v_fmac_f32_e32 v32, v40, v49
	v_fmac_f32_e32 v33, v41, v50
	v_mul_f32_e32 v49, 0x3d372713, v32
	v_mul_f32_e32 v50, 0x3d372713, v33
	v_mul_f32_e32 v49, v32, v49
	v_mul_f32_e32 v50, v33, v50
	v_fma_f32 v49, v32, v49, v32
	v_fma_f32 v50, v33, v50, v33
	v_mul_f32_e32 v49, 0x3f4c422a, v49
	v_mul_f32_e32 v50, 0x3f4c422a, v50
	v_add_f32_e32 v49, v49, v49
	v_add_f32_e32 v50, v50, v50
	v_mul_f32_e32 v49, 0xbfb8aa3b, v49
	v_mul_f32_e32 v50, 0xbfb8aa3b, v50
	v_rcp_f32_e32 v48, v48
	v_exp_f32_e32 v49, v49
	v_exp_f32_e32 v50, v50
	v_mul_f32_e32 v52, v36, v52
	v_mul_f32_e32 v39, v39, v48
	v_add_f32_e32 v48, 1.0, v49
	v_add_f32_e32 v49, 1.0, v50
	v_lshlrev_b32_e32 v50, 16, v51
	v_and_b32_e32 v51, 0xffff0000, v51
	v_fmac_f32_e32 v35, v43, v51
	v_fmac_f32_e32 v38, v46, v53
	v_fmac_f32_e32 v34, v42, v50
	v_mul_f32_e32 v51, 0x3d372713, v35
	v_fma_f32 v52, v36, v52, v36
	v_mul_f32_e32 v53, 0x3d372713, v38
	v_mul_f32_e32 v50, 0x3d372713, v34
	v_mul_f32_e32 v51, v35, v51
	v_mul_f32_e32 v52, 0x3f4c422a, v52
	v_mul_f32_e32 v53, v38, v53
	v_mul_f32_e32 v50, v34, v50
	v_fma_f32 v51, v35, v51, v35
	v_add_f32_e32 v52, v52, v52
	v_fma_f32 v53, v38, v53, v38
	v_fma_f32 v50, v34, v50, v34
	v_mul_f32_e32 v51, 0x3f4c422a, v51
	v_mul_f32_e32 v52, 0xbfb8aa3b, v52
	v_mul_f32_e32 v53, 0x3f4c422a, v53
	v_mul_f32_e32 v50, 0x3f4c422a, v50
	v_add_f32_e32 v51, v51, v51
	v_exp_f32_e32 v52, v52
	v_add_f32_e32 v53, v53, v53
	v_add_f32_e32 v50, v50, v50
	v_mul_f32_e32 v51, 0xbfb8aa3b, v51
	v_mul_f32_e32 v53, 0xbfb8aa3b, v53
	v_mul_f32_e32 v50, 0xbfb8aa3b, v50
	v_exp_f32_e32 v51, v51
	v_exp_f32_e32 v53, v53
	v_exp_f32_e32 v50, v50
	v_add_f32_e32 v52, 1.0, v52
	v_rcp_f32_e32 v52, v52
	v_add_f32_e32 v51, 1.0, v51
	v_add_f32_e32 v53, 1.0, v53
	v_rcp_f32_e32 v48, v48
	v_add_f32_e32 v50, 1.0, v50
	v_rcp_f32_e32 v51, v51
	v_rcp_f32_e32 v53, v53
	v_rcp_f32_e32 v49, v49
	v_rcp_f32_e32 v50, v50
	v_mul_f32_e32 v36, v36, v52
	v_mul_f32_e32 v48, v32, v48
	v_mul_f32_e32 v35, v35, v51
	v_cvt_pk_bf16_f32 v32, v36, v37
	v_add_u32_e32 v36, 0x910000, v156
	v_mul_f32_e32 v38, v38, v53
	v_mul_f32_e32 v49, v33, v49
	v_mul_f32_e32 v50, v34, v50
	v_cvt_pk_bf16_f32 v33, v38, v39
	v_cvt_pk_bf16_f32 v34, v48, v49
	v_cvt_pk_bf16_f32 v35, v50, v35
	global_store_dwordx4 v36, v[32:35], s[12:13]
	v_cndmask_b32_e64 v39, v28, v20, s[8:9]
	v_mov_b32_e32 v48, 0
	v_add_u32_e32 v32, 0x1e000, v157
	s_waitcnt vmcnt(15)
	s_nop 1
	v_mov_b32_e32 v32, v232
	v_mov_b32_e32 v33, v233
	v_mov_b32_e32 v34, v234
	v_mov_b32_e32 v35, v235
	v_cndmask_b32_e64 v38, v29, v21, s[8:9]
	v_mov_b32_dpp v48, v39 quad_perm:[1,0,3,2] row_mask:0xf bank_mask:0xf
	v_mov_b32_e32 v39, 0
	v_cndmask_b32_e64 v51, v24, v16, s[8:9]
	v_mov_b32_e32 v52, 0
	v_cndmask_b32_e64 v37, v30, v22, s[8:9]
	v_mov_b32_dpp v39, v38 quad_perm:[1,0,3,2] row_mask:0xf bank_mask:0xf
	v_mov_b32_e32 v38, 0
	v_cndmask_b32_e64 v50, v25, v17, s[8:9]
	v_mov_b32_dpp v52, v51 quad_perm:[1,0,3,2] row_mask:0xf bank_mask:0xf
	v_mov_b32_e32 v51, 0
	v_cndmask_b32_e64 v36, v31, v23, s[8:9]
	v_mov_b32_dpp v38, v37 quad_perm:[1,0,3,2] row_mask:0xf bank_mask:0xf
	v_mov_b32_e32 v37, 0
	v_cndmask_b32_e64 v49, v26, v18, s[8:9]
	v_mov_b32_dpp v51, v50 quad_perm:[1,0,3,2] row_mask:0xf bank_mask:0xf
	v_mov_b32_e32 v50, 0
	v_mov_b32_dpp v37, v36 quad_perm:[1,0,3,2] row_mask:0xf bank_mask:0xf
	v_cndmask_b32_e64 v36, v27, v19, s[8:9]
	v_mov_b32_dpp v50, v49 quad_perm:[1,0,3,2] row_mask:0xf bank_mask:0xf
	v_mov_b32_e32 v49, 0
	v_cndmask_b32_e64 v29, v39, v29, s[8:9]
	v_cndmask_b32_e64 v31, v37, v31, s[8:9]
	v_mov_b32_dpp v49, v36 quad_perm:[1,0,3,2] row_mask:0xf bank_mask:0xf
	v_cndmask_b32_e64 v25, v51, v25, s[8:9]
	v_cndmask_b32_e64 v24, v52, v24, s[8:9]
	v_cndmask_b32_e64 v28, v48, v28, s[8:9]
	v_cndmask_b32_e64 v27, v49, v27, s[8:9]
	v_cndmask_b32_e64 v30, v38, v30, s[8:9]
	v_cndmask_b32_e64 v26, v50, v26, s[8:9]
	v_add_u32_e32 v53, 0xa00000, v156
	v_cndmask_b32_e64 v21, v21, v39, s[8:9]
	v_cndmask_b32_e64 v23, v23, v37, s[8:9]
	v_cndmask_b32_e64 v17, v17, v51, s[8:9]
	v_cndmask_b32_e64 v16, v16, v52, s[8:9]
	v_cndmask_b32_e64 v20, v20, v48, s[8:9]
	v_cndmask_b32_e64 v19, v19, v49, s[8:9]
	v_cndmask_b32_e64 v22, v22, v38, s[8:9]
	v_cndmask_b32_e64 v18, v18, v50, s[8:9]
	v_lshlrev_b32_e32 v36, 16, v32
	v_and_b32_e32 v32, 0xffff0000, v32
	v_fmac_f32_e32 v29, v45, v32
	v_mul_f32_e32 v32, 0x3d372713, v29
	v_mul_f32_e32 v32, v29, v32
	v_fma_f32 v32, v29, v32, v29
	v_mul_f32_e32 v32, 0x3f4c422a, v32
	v_lshlrev_b32_e32 v54, 16, v33
	v_and_b32_e32 v33, 0xffff0000, v33
	v_add_f32_e32 v32, v32, v32
	v_fmac_f32_e32 v31, v47, v33
	v_mul_f32_e32 v32, 0xbfb8aa3b, v32
	v_mul_f32_e32 v33, 0x3d372713, v31
	v_exp_f32_e32 v32, v32
; __device__ __forceinline__ float fast_sigmoid(float x) { return __builtin_amdgcn_rcpf(1.0f + fast_exp(-x)); }
; __device__ __forceinline__ float gelu_tanh(float x) {
;     const float a = 0.7978845608028654f * (x + 0.044715f * x * x * x);
;     return x * fast_sigmoid(2.0f * a);
; }
;     __device__ __forceinline__ void operator()(const f32x4 (&acc)[2][2][4][2], const Unit& u, int wr, int wc, int fr, int fq, const EpiCtx& X) const {
;     ...
;         EPI_PIECES({ const unsigned uoff = ulo + (unsigned)(rl * UA_LD) * 2u, goff = glo + (unsigned)(rl * 16 * W_SSM) * 2u;
;             S2_ONE(p1a, p1b, uoff, goff); S2_ONE(p2a, p2b, uoff + UA_LD * 2, goff + 16 * W_SSM * 2); })
	v_mul_f32_e32 v33, v31, v33
	v_fma_f32 v33, v31, v33, v31
	v_mul_f32_e32 v33, 0x3f4c422a, v33
	v_add_f32_e32 v33, v33, v33
	v_add_f32_e32 v32, 1.0, v32
	v_mul_f32_e32 v33, 0xbfb8aa3b, v33
	v_rcp_f32_e32 v32, v32
	v_exp_f32_e32 v33, v33
	v_fmac_f32_e32 v28, v44, v36
	v_mul_f32_e32 v36, 0x3d372713, v28
	v_mul_f32_e32 v29, v29, v32
	v_add_f32_e32 v32, 1.0, v33
	v_lshlrev_b32_e32 v33, 16, v34
	v_and_b32_e32 v34, 0xffff0000, v34
	v_fmac_f32_e32 v24, v40, v33
	v_fmac_f32_e32 v25, v41, v34
	v_mul_f32_e32 v33, 0x3d372713, v24
	v_mul_f32_e32 v34, 0x3d372713, v25
	v_mul_f32_e32 v33, v24, v33
	v_mul_f32_e32 v34, v25, v34
	v_fma_f32 v33, v24, v33, v24
	v_fma_f32 v34, v25, v34, v25
	v_mul_f32_e32 v33, 0x3f4c422a, v33
	v_mul_f32_e32 v34, 0x3f4c422a, v34
	v_add_f32_e32 v33, v33, v33
	v_add_f32_e32 v34, v34, v34
	v_mul_f32_e32 v33, 0xbfb8aa3b, v33
	v_mul_f32_e32 v34, 0xbfb8aa3b, v34
	v_rcp_f32_e32 v32, v32
	v_exp_f32_e32 v33, v33
	v_exp_f32_e32 v34, v34
	v_fmac_f32_e32 v30, v46, v54
	v_mul_f32_e32 v31, v31, v32
	v_add_f32_e32 v32, 1.0, v33
	v_add_f32_e32 v33, 1.0, v34
	v_lshlrev_b32_e32 v34, 16, v35
	v_and_b32_e32 v35, 0xffff0000, v35
	v_fmac_f32_e32 v27, v43, v35
	v_fmac_f32_e32 v26, v42, v34
	v_mul_f32_e32 v35, 0x3d372713, v27
	v_mul_f32_e32 v36, v28, v36
	v_mul_f32_e32 v54, 0x3d372713, v30
	v_mul_f32_e32 v34, 0x3d372713, v26
	v_mul_f32_e32 v35, v27, v35
	v_fma_f32 v36, v28, v36, v28
	v_mul_f32_e32 v54, v30, v54
	v_mul_f32_e32 v34, v26, v34
	v_fma_f32 v35, v27, v35, v27
	v_mul_f32_e32 v36, 0x3f4c422a, v36
	v_fma_f32 v54, v30, v54, v30
	v_fma_f32 v34, v26, v34, v26
	v_mul_f32_e32 v35, 0x3f4c422a, v35
	v_add_f32_e32 v36, v36, v36
	v_mul_f32_e32 v54, 0x3f4c422a, v54
	v_mul_f32_e32 v34, 0x3f4c422a, v34
	v_add_f32_e32 v35, v35, v35
	v_mul_f32_e32 v36, 0xbfb8aa3b, v36
	v_add_f32_e32 v54, v54, v54
	v_add_f32_e32 v34, v34, v34
	v_mul_f32_e32 v35, 0xbfb8aa3b, v35
	v_exp_f32_e32 v36, v36
	v_mul_f32_e32 v54, 0xbfb8aa3b, v54
	v_mul_f32_e32 v34, 0xbfb8aa3b, v34
	v_exp_f32_e32 v35, v35
	v_exp_f32_e32 v54, v54
	v_exp_f32_e32 v34, v34
	v_add_f32_e32 v36, 1.0, v36
	v_add_f32_e32 v35, 1.0, v35
	v_rcp_f32_e32 v36, v36
	v_add_f32_e32 v54, 1.0, v54
	v_rcp_f32_e32 v32, v32
	v_add_f32_e32 v34, 1.0, v34
	v_rcp_f32_e32 v35, v35
	v_rcp_f32_e32 v54, v54
	v_rcp_f32_e32 v33, v33
	v_rcp_f32_e32 v34, v34
	v_mul_f32_e32 v28, v28, v36
	v_mul_f32_e32 v32, v24, v32
	v_mul_f32_e32 v27, v27, v35
	v_cvt_pk_bf16_f32 v24, v28, v29
	v_mul_f32_e32 v30, v30, v54
	v_mul_f32_e32 v33, v25, v33
	v_mul_f32_e32 v34, v26, v34
	v_cvt_pk_bf16_f32 v25, v30, v31
	v_cvt_pk_bf16_f32 v26, v32, v33
	v_cvt_pk_bf16_f32 v27, v34, v27
	global_store_dwordx4 v53, v[24:27], s[12:13]
	s_nop 1
	v_add_u32_e32 v24, 0x1e300, v157
	s_waitcnt vmcnt(15)
	s_nop 1
	v_mov_b32_e32 v24, v236
	v_mov_b32_e32 v25, v237
	v_mov_b32_e32 v26, v238
	v_mov_b32_e32 v27, v239
	v_lshlrev_b32_e32 v28, 16, v24
	v_and_b32_e32 v24, 0xffff0000, v24
	v_fmac_f32_e32 v21, v45, v24
	v_mul_f32_e32 v24, 0x3d372713, v21
	v_mul_f32_e32 v24, v21, v24
	v_fma_f32 v24, v21, v24, v21
	v_mul_f32_e32 v24, 0x3f4c422a, v24
	v_lshlrev_b32_e32 v29, 16, v25
	v_and_b32_e32 v25, 0xffff0000, v25
	v_add_f32_e32 v24, v24, v24
	v_fmac_f32_e32 v23, v47, v25
	v_mul_f32_e32 v24, 0xbfb8aa3b, v24
	v_mul_f32_e32 v25, 0x3d372713, v23
	v_exp_f32_e32 v24, v24
	v_mul_f32_e32 v25, v23, v25
	v_fma_f32 v25, v23, v25, v23
	v_mul_f32_e32 v25, 0x3f4c422a, v25
	v_add_f32_e32 v25, v25, v25
	v_add_f32_e32 v24, 1.0, v24
	v_mul_f32_e32 v25, 0xbfb8aa3b, v25
	v_rcp_f32_e32 v24, v24
	v_exp_f32_e32 v25, v25
	v_fmac_f32_e32 v20, v44, v28
	v_mul_f32_e32 v28, 0x3d372713, v20
	v_mul_f32_e32 v21, v21, v24
	v_add_f32_e32 v24, 1.0, v25
	v_lshlrev_b32_e32 v25, 16, v26
	v_and_b32_e32 v26, 0xffff0000, v26
	v_fmac_f32_e32 v16, v40, v25
	v_fmac_f32_e32 v17, v41, v26
	v_mul_f32_e32 v25, 0x3d372713, v16
	v_mul_f32_e32 v26, 0x3d372713, v17
	v_mul_f32_e32 v25, v16, v25
	v_mul_f32_e32 v26, v17, v26
	v_fma_f32 v25, v16, v25, v16
	v_fma_f32 v26, v17, v26, v17
	v_mul_f32_e32 v25, 0x3f4c422a, v25
	v_mul_f32_e32 v26, 0x3f4c422a, v26
	v_add_f32_e32 v25, v25, v25
	v_add_f32_e32 v26, v26, v26
	v_mul_f32_e32 v25, 0xbfb8aa3b, v25
	v_mul_f32_e32 v26, 0xbfb8aa3b, v26
	v_rcp_f32_e32 v24, v24
	v_exp_f32_e32 v25, v25
	v_exp_f32_e32 v26, v26
	v_mul_f32_e32 v28, v20, v28
	v_mul_f32_e32 v23, v23, v24
	v_add_f32_e32 v24, 1.0, v25
	v_add_f32_e32 v25, 1.0, v26
	v_lshlrev_b32_e32 v26, 16, v27
	v_and_b32_e32 v27, 0xffff0000, v27
	v_fmac_f32_e32 v19, v43, v27
	v_fmac_f32_e32 v22, v46, v29
	v_fmac_f32_e32 v18, v42, v26
	v_mul_f32_e32 v27, 0x3d372713, v19
	v_fma_f32 v28, v20, v28, v20
	v_mul_f32_e32 v29, 0x3d372713, v22
	v_mul_f32_e32 v26, 0x3d372713, v18
	v_mul_f32_e32 v27, v19, v27
	v_mul_f32_e32 v28, 0x3f4c422a, v28
	v_mul_f32_e32 v29, v22, v29
	v_mul_f32_e32 v26, v18, v26
	v_fma_f32 v27, v19, v27, v19
	v_add_f32_e32 v28, v28, v28
	v_fma_f32 v29, v22, v29, v22
	v_fma_f32 v26, v18, v26, v18
	v_mul_f32_e32 v27, 0x3f4c422a, v27
	v_mul_f32_e32 v28, 0xbfb8aa3b, v28
	v_mul_f32_e32 v29, 0x3f4c422a, v29
	v_mul_f32_e32 v26, 0x3f4c422a, v26
	v_add_f32_e32 v27, v27, v27
	v_exp_f32_e32 v28, v28
	v_add_f32_e32 v29, v29, v29
	v_add_f32_e32 v26, v26, v26
	v_mul_f32_e32 v27, 0xbfb8aa3b, v27
	v_mul_f32_e32 v29, 0xbfb8aa3b, v29
	v_mul_f32_e32 v26, 0xbfb8aa3b, v26
	v_exp_f32_e32 v27, v27
	v_exp_f32_e32 v29, v29
	v_exp_f32_e32 v26, v26
	v_add_f32_e32 v28, 1.0, v28
	v_rcp_f32_e32 v28, v28
	v_add_f32_e32 v27, 1.0, v27
	v_add_f32_e32 v29, 1.0, v29
	v_rcp_f32_e32 v24, v24
	v_add_f32_e32 v26, 1.0, v26
	v_rcp_f32_e32 v27, v27
	v_rcp_f32_e32 v29, v29
	v_rcp_f32_e32 v25, v25
	v_rcp_f32_e32 v26, v26
	v_mul_f32_e32 v20, v20, v28
	v_mul_f32_e32 v24, v16, v24
	v_mul_f32_e32 v19, v19, v27
	v_cvt_pk_bf16_f32 v16, v20, v21
	v_add_u32_e32 v20, 0xa10000, v156
	v_mul_f32_e32 v22, v22, v29
	v_mul_f32_e32 v25, v17, v25
	v_mul_f32_e32 v26, v18, v26
	v_cvt_pk_bf16_f32 v17, v22, v23
	v_cvt_pk_bf16_f32 v18, v24, v25
	v_cvt_pk_bf16_f32 v19, v26, v19
	global_store_dwordx4 v20, v[16:19], s[12:13]
	v_cndmask_b32_e64 v23, v12, v4, s[8:9]
	v_mov_b32_e32 v24, 0
	v_add_u32_e32 v16, 0x21000, v157
	s_waitcnt vmcnt(15)
;     __device__ __forceinline__ void operator()(const f32x4 (&acc)[2][2][4][2], const Unit& u, int wr, int wc, int fr, int fq, const EpiCtx& X) const {
;     ...
;         EPI_PIECES({ const unsigned uoff = ulo + (unsigned)(rl * UA_LD) * 2u, goff = glo + (unsigned)(rl * 16 * W_SSM) * 2u;
;             S2_ONE(p1a, p1b, uoff, goff); S2_ONE(p2a, p2b, uoff + UA_LD * 2, goff + 16 * W_SSM * 2); })
	s_nop 1
	v_mov_b32_e32 v16, v240
	v_mov_b32_e32 v17, v241
	v_mov_b32_e32 v18, v242
	v_mov_b32_e32 v19, v243
	v_cndmask_b32_e64 v22, v13, v5, s[8:9]
	v_mov_b32_dpp v24, v23 quad_perm:[1,0,3,2] row_mask:0xf bank_mask:0xf
	v_mov_b32_e32 v23, 0
	v_cndmask_b32_e64 v27, v8, v0, s[8:9]
	v_mov_b32_e32 v28, 0
	v_cndmask_b32_e64 v21, v14, v6, s[8:9]
	v_mov_b32_dpp v23, v22 quad_perm:[1,0,3,2] row_mask:0xf bank_mask:0xf
	v_mov_b32_e32 v22, 0
	v_cndmask_b32_e64 v26, v9, v1, s[8:9]
	v_mov_b32_dpp v28, v27 quad_perm:[1,0,3,2] row_mask:0xf bank_mask:0xf
	v_mov_b32_e32 v27, 0
	v_cndmask_b32_e64 v20, v15, v7, s[8:9]
	v_mov_b32_dpp v22, v21 quad_perm:[1,0,3,2] row_mask:0xf bank_mask:0xf
	v_mov_b32_e32 v21, 0
	v_cndmask_b32_e64 v25, v10, v2, s[8:9]
	v_mov_b32_dpp v27, v26 quad_perm:[1,0,3,2] row_mask:0xf bank_mask:0xf
	v_mov_b32_e32 v26, 0
	v_mov_b32_dpp v21, v20 quad_perm:[1,0,3,2] row_mask:0xf bank_mask:0xf
	v_cndmask_b32_e64 v20, v11, v3, s[8:9]
	v_mov_b32_dpp v26, v25 quad_perm:[1,0,3,2] row_mask:0xf bank_mask:0xf
	v_mov_b32_e32 v25, 0
	v_cndmask_b32_e64 v13, v23, v13, s[8:9]
	v_cndmask_b32_e64 v15, v21, v15, s[8:9]
	v_mov_b32_dpp v25, v20 quad_perm:[1,0,3,2] row_mask:0xf bank_mask:0xf
	v_cndmask_b32_e64 v9, v27, v9, s[8:9]
	v_cndmask_b32_e64 v8, v28, v8, s[8:9]
	v_cndmask_b32_e64 v12, v24, v12, s[8:9]
	v_cndmask_b32_e64 v11, v25, v11, s[8:9]
	v_cndmask_b32_e64 v14, v22, v14, s[8:9]
	v_cndmask_b32_e64 v10, v26, v10, s[8:9]
	v_add_u32_e32 v29, 0xb00000, v156
	v_cndmask_b32_e64 v5, v5, v23, s[8:9]
	v_cndmask_b32_e64 v7, v7, v21, s[8:9]
	v_cndmask_b32_e64 v1, v1, v27, s[8:9]
	v_cndmask_b32_e64 v0, v0, v28, s[8:9]
	v_cndmask_b32_e64 v4, v4, v24, s[8:9]
	v_cndmask_b32_e64 v3, v3, v25, s[8:9]
	v_cndmask_b32_e64 v6, v6, v22, s[8:9]
	v_cndmask_b32_e64 v2, v2, v26, s[8:9]
	v_lshlrev_b32_e32 v20, 16, v16
	v_and_b32_e32 v16, 0xffff0000, v16
	v_fmac_f32_e32 v13, v45, v16
	v_mul_f32_e32 v16, 0x3d372713, v13
	v_mul_f32_e32 v16, v13, v16
	v_fma_f32 v16, v13, v16, v13
	v_mul_f32_e32 v16, 0x3f4c422a, v16
	v_lshlrev_b32_e32 v30, 16, v17
	v_and_b32_e32 v17, 0xffff0000, v17
	v_add_f32_e32 v16, v16, v16
	v_fmac_f32_e32 v15, v47, v17
	v_mul_f32_e32 v16, 0xbfb8aa3b, v16
	v_mul_f32_e32 v17, 0x3d372713, v15
	v_exp_f32_e32 v16, v16
	v_mul_f32_e32 v17, v15, v17
	v_fma_f32 v17, v15, v17, v15
	v_mul_f32_e32 v17, 0x3f4c422a, v17
	v_add_f32_e32 v17, v17, v17
	v_add_f32_e32 v16, 1.0, v16
	v_mul_f32_e32 v17, 0xbfb8aa3b, v17
	v_rcp_f32_e32 v16, v16
	v_exp_f32_e32 v17, v17
	v_fmac_f32_e32 v12, v44, v20
	v_mul_f32_e32 v20, 0x3d372713, v12
	v_mul_f32_e32 v13, v13, v16
	v_add_f32_e32 v16, 1.0, v17
	v_lshlrev_b32_e32 v17, 16, v18
	v_and_b32_e32 v18, 0xffff0000, v18
	v_fmac_f32_e32 v8, v40, v17
	v_fmac_f32_e32 v9, v41, v18
	v_mul_f32_e32 v17, 0x3d372713, v8
	v_mul_f32_e32 v18, 0x3d372713, v9
	v_mul_f32_e32 v17, v8, v17
	v_mul_f32_e32 v18, v9, v18
	v_fma_f32 v17, v8, v17, v8
	v_fma_f32 v18, v9, v18, v9
	v_mul_f32_e32 v17, 0x3f4c422a, v17
	v_mul_f32_e32 v18, 0x3f4c422a, v18
	v_add_f32_e32 v17, v17, v17
	v_add_f32_e32 v18, v18, v18
	v_mul_f32_e32 v17, 0xbfb8aa3b, v17
	v_mul_f32_e32 v18, 0xbfb8aa3b, v18
	v_rcp_f32_e32 v16, v16
	v_exp_f32_e32 v17, v17
	v_exp_f32_e32 v18, v18
	v_fmac_f32_e32 v14, v46, v30
	v_mul_f32_e32 v15, v15, v16
	v_add_f32_e32 v16, 1.0, v17
	v_add_f32_e32 v17, 1.0, v18
	v_lshlrev_b32_e32 v18, 16, v19
	v_and_b32_e32 v19, 0xffff0000, v19
	v_fmac_f32_e32 v11, v43, v19
	v_fmac_f32_e32 v10, v42, v18
	v_mul_f32_e32 v19, 0x3d372713, v11
	v_mul_f32_e32 v20, v12, v20
	v_mul_f32_e32 v30, 0x3d372713, v14
	v_mul_f32_e32 v18, 0x3d372713, v10
	v_mul_f32_e32 v19, v11, v19
	v_fma_f32 v20, v12, v20, v12
	v_mul_f32_e32 v30, v14, v30
	v_mul_f32_e32 v18, v10, v18
	v_fma_f32 v19, v11, v19, v11
	v_mul_f32_e32 v20, 0x3f4c422a, v20
	v_fma_f32 v30, v14, v30, v14
	v_fma_f32 v18, v10, v18, v10
	v_mul_f32_e32 v19, 0x3f4c422a, v19
	v_add_f32_e32 v20, v20, v20
	v_mul_f32_e32 v30, 0x3f4c422a, v30
	v_mul_f32_e32 v18, 0x3f4c422a, v18
	v_add_f32_e32 v19, v19, v19
	v_mul_f32_e32 v20, 0xbfb8aa3b, v20
	v_add_f32_e32 v30, v30, v30
	v_add_f32_e32 v18, v18, v18
	v_mul_f32_e32 v19, 0xbfb8aa3b, v19
	v_exp_f32_e32 v20, v20
	v_mul_f32_e32 v30, 0xbfb8aa3b, v30
	v_mul_f32_e32 v18, 0xbfb8aa3b, v18
	v_exp_f32_e32 v19, v19
	v_exp_f32_e32 v30, v30
	v_exp_f32_e32 v18, v18
	v_add_f32_e32 v20, 1.0, v20
	v_add_f32_e32 v19, 1.0, v19
	v_rcp_f32_e32 v20, v20
	v_add_f32_e32 v30, 1.0, v30
	v_rcp_f32_e32 v16, v16
	v_add_f32_e32 v18, 1.0, v18
	v_rcp_f32_e32 v19, v19
	v_rcp_f32_e32 v30, v30
	v_rcp_f32_e32 v17, v17
	v_rcp_f32_e32 v18, v18
	v_mul_f32_e32 v12, v12, v20
	v_mul_f32_e32 v16, v8, v16
	v_mul_f32_e32 v11, v11, v19
	v_cvt_pk_bf16_f32 v8, v12, v13
	v_mul_f32_e32 v14, v14, v30
	v_mul_f32_e32 v17, v9, v17
	v_mul_f32_e32 v18, v10, v18
	v_cvt_pk_bf16_f32 v9, v14, v15
	v_cvt_pk_bf16_f32 v10, v16, v17
	v_cvt_pk_bf16_f32 v11, v18, v11
	global_store_dwordx4 v29, v[8:11], s[12:13]
	s_nop 1
	v_add_u32_e32 v8, 0x21300, v157
	s_waitcnt vmcnt(15)
; #define PG8_BAR __builtin_amdgcn_s_barrier()
; template <class Epi, class Sched, bool ALIGN_EPI>
; __device__ __forceinline__ void gemm_phase(LAS unsigned char* lds, const Gemm g, const Sched& S, const Epi& E, const int wid) {
;     ...
;         if (!has_next) break;
; #pragma unroll
;         for (int a = 0; a < 2; ++a)
; #pragma unroll
;             for (int b = 0; b < 2; ++b)
; #pragma unroll
;                 for (int m = 0; m < 4; ++m)
; #pragma unroll
;                     for (int n = 0; n < 2; ++n) acc[a][b][m][n] = (f32x4){0.f, 0.f, 0.f, 0.f};
;         cur = nxt; cA = nA; cB = nB; ++ui;
;         if constexpr (ALIGN_EPI) { if (wr == 1) PG8_BAR; }
;     __device__ __forceinline__ void operator()(const f32x4 (&acc)[2][2][4][2], const Unit& u, int wr, int wc, int fr, int fq, const EpiCtx& X) const {
;     ...
;         EPI_PIECES({ const unsigned uoff = ulo + (unsigned)(rl * UA_LD) * 2u, goff = glo + (unsigned)(rl * 16 * W_SSM) * 2u;
;             S2_ONE(p1a, p1b, uoff, goff); S2_ONE(p2a, p2b, uoff + UA_LD * 2, goff + 16 * W_SSM * 2); })
	s_nop 1
	v_mov_b32_e32 v8, v244
	v_mov_b32_e32 v9, v245
	v_mov_b32_e32 v10, v246
	v_mov_b32_e32 v11, v247
	v_lshlrev_b32_e32 v12, 16, v8
	v_and_b32_e32 v8, 0xffff0000, v8
	v_fmac_f32_e32 v5, v45, v8
	v_mul_f32_e32 v8, 0x3d372713, v5
	v_mul_f32_e32 v8, v5, v8
	v_fma_f32 v8, v5, v8, v5
	v_mul_f32_e32 v8, 0x3f4c422a, v8
	v_lshlrev_b32_e32 v13, 16, v9
	v_and_b32_e32 v9, 0xffff0000, v9
	v_add_f32_e32 v8, v8, v8
	v_fmac_f32_e32 v7, v47, v9
	v_mul_f32_e32 v8, 0xbfb8aa3b, v8
	v_mul_f32_e32 v9, 0x3d372713, v7
	v_exp_f32_e32 v8, v8
	v_mul_f32_e32 v9, v7, v9
	v_fma_f32 v9, v7, v9, v7
	v_mul_f32_e32 v9, 0x3f4c422a, v9
	v_add_f32_e32 v9, v9, v9
	v_add_f32_e32 v8, 1.0, v8
	v_mul_f32_e32 v9, 0xbfb8aa3b, v9
	v_rcp_f32_e32 v8, v8
	v_exp_f32_e32 v9, v9
	v_fmac_f32_e32 v4, v44, v12
	v_mul_f32_e32 v12, 0x3d372713, v4
	v_mul_f32_e32 v5, v5, v8
	v_add_f32_e32 v8, 1.0, v9
	v_lshlrev_b32_e32 v9, 16, v10
	v_and_b32_e32 v10, 0xffff0000, v10
	v_fmac_f32_e32 v0, v40, v9
	v_fmac_f32_e32 v1, v41, v10
	v_mul_f32_e32 v9, 0x3d372713, v0
	v_mul_f32_e32 v10, 0x3d372713, v1
	v_mul_f32_e32 v9, v0, v9
	v_mul_f32_e32 v10, v1, v10
	v_fma_f32 v9, v0, v9, v0
	v_fma_f32 v10, v1, v10, v1
	v_mul_f32_e32 v9, 0x3f4c422a, v9
	v_mul_f32_e32 v10, 0x3f4c422a, v10
	v_add_f32_e32 v9, v9, v9
	v_add_f32_e32 v10, v10, v10
	v_mul_f32_e32 v9, 0xbfb8aa3b, v9
	v_mul_f32_e32 v10, 0xbfb8aa3b, v10
	v_rcp_f32_e32 v8, v8
	v_exp_f32_e32 v9, v9
	v_exp_f32_e32 v10, v10
	v_mul_f32_e32 v12, v4, v12
	v_mul_f32_e32 v7, v7, v8
	v_add_f32_e32 v8, 1.0, v9
	v_add_f32_e32 v9, 1.0, v10
	v_lshlrev_b32_e32 v10, 16, v11
	v_and_b32_e32 v11, 0xffff0000, v11
	v_fmac_f32_e32 v3, v43, v11
	v_fmac_f32_e32 v6, v46, v13
	v_fmac_f32_e32 v2, v42, v10
	v_mul_f32_e32 v11, 0x3d372713, v3
	v_fma_f32 v12, v4, v12, v4
	v_mul_f32_e32 v13, 0x3d372713, v6
	v_mul_f32_e32 v10, 0x3d372713, v2
	v_mul_f32_e32 v11, v3, v11
	v_mul_f32_e32 v12, 0x3f4c422a, v12
	v_mul_f32_e32 v13, v6, v13
	v_mul_f32_e32 v10, v2, v10
	v_fma_f32 v11, v3, v11, v3
	v_add_f32_e32 v12, v12, v12
	v_fma_f32 v13, v6, v13, v6
	v_fma_f32 v10, v2, v10, v2
	v_mul_f32_e32 v11, 0x3f4c422a, v11
	v_mul_f32_e32 v12, 0xbfb8aa3b, v12
	v_mul_f32_e32 v13, 0x3f4c422a, v13
	v_mul_f32_e32 v10, 0x3f4c422a, v10
	v_add_f32_e32 v11, v11, v11
	v_exp_f32_e32 v12, v12
	v_add_f32_e32 v13, v13, v13
	v_add_f32_e32 v10, v10, v10
	v_mul_f32_e32 v11, 0xbfb8aa3b, v11
	v_mul_f32_e32 v13, 0xbfb8aa3b, v13
	v_mul_f32_e32 v10, 0xbfb8aa3b, v10
	v_exp_f32_e32 v11, v11
	v_exp_f32_e32 v13, v13
	v_exp_f32_e32 v10, v10
	v_add_f32_e32 v12, 1.0, v12
	v_rcp_f32_e32 v12, v12
	v_add_f32_e32 v11, 1.0, v11
	v_add_f32_e32 v13, 1.0, v13
	v_rcp_f32_e32 v8, v8
	v_add_f32_e32 v10, 1.0, v10
	v_rcp_f32_e32 v11, v11
	v_rcp_f32_e32 v13, v13
	v_rcp_f32_e32 v9, v9
	v_rcp_f32_e32 v10, v10
	v_mul_f32_e32 v4, v4, v12
	v_mul_f32_e32 v8, v0, v8
	v_mul_f32_e32 v3, v3, v11
	v_cvt_pk_bf16_f32 v0, v4, v5
	v_add_u32_e32 v4, 0xb10000, v156
	v_mul_f32_e32 v6, v6, v13
	v_mul_f32_e32 v9, v1, v9
	v_mul_f32_e32 v10, v2, v10
	v_cvt_pk_bf16_f32 v1, v6, v7
	v_cvt_pk_bf16_f32 v2, v8, v9
	v_cvt_pk_bf16_f32 v3, v10, v3
	global_store_dwordx4 v4, v[0:3], s[12:13]
	s_cbranch_vccnz .LBB0_276
	s_and_b64 vcc, exec, s[6:7]
	s_cbranch_vccnz .LBB0_275
	s_barrier
	s_branch .LBB0_275
